# b7 + dropped per-iteration vmcnt(0) at K-loop heads of INCV/UP0/KVQG/UP1
# speedup vs baseline: 1.0204x; 1.0047x over previous
.LBB0_191:
	ds_read_b128 v[48:51], v147
	ds_read_b128 v[132:135], v147 offset:1024
	ds_read_b128 v[162:165], v147 offset:2048
	ds_read_b128 v[166:169], v147 offset:3072
	s_add_u32 s34, s8, 0x100
	s_addc_u32 s35, s9, 0
	s_cmp_eq_u32 s70, 12
	s_cselect_b32 s39, s62, s35
	s_cselect_b32 s38, s63, s34
	s_cselect_b32 s37, s15, s69
	s_cselect_b32 s36, s67, s68
	s_mov_b32 m0, s57
	v_lshl_add_u64 v[186:187], s[8:9], 0, v[150:151]
	ds_read_b128 v[170:173], v159
	ds_read_b128 v[174:177], v159 offset:1024
	ds_read_b128 v[178:181], v159 offset:2048
	ds_read_b128 v[182:185], v159 offset:3072
	ds_read_b128 v[190:193], v159 offset:4096
	ds_read_b128 v[194:197], v159 offset:5120
	ds_read_b128 v[198:201], v159 offset:6144
	ds_read_b128 v[202:205], v159 offset:7168
	global_load_lds_dwordx4 v[186:187], off
	v_lshl_add_u64 v[186:187], s[8:9], 0, v[152:153]
	s_mov_b32 m0, s58
	s_nop 0
	global_load_lds_dwordx4 v[186:187], off
	s_waitcnt lgkmcnt(8)
	s_barrier
	s_waitcnt lgkmcnt(0)
	s_setprio 1
	s_waitcnt lgkmcnt(0)
	v_mfma_f32_16x16x32_bf16 v[72:75], v[48:51], v[170:173], v[72:75]
	v_mfma_f32_16x16x32_bf16 v[28:31], v[162:165], v[170:173], v[28:31]
	v_mfma_f32_16x16x32_bf16 v[64:67], v[48:51], v[178:181], v[64:67]
	v_mfma_f32_16x16x32_bf16 v[24:27], v[162:165], v[178:181], v[24:27]
	v_mfma_f32_16x16x32_bf16 v[128:131], v[48:51], v[190:193], v[128:131]
	v_mfma_f32_16x16x32_bf16 v[124:127], v[162:165], v[190:193], v[124:127]
	v_mfma_f32_16x16x32_bf16 v[120:123], v[48:51], v[198:201], v[120:123]
	v_mfma_f32_16x16x32_bf16 v[116:119], v[162:165], v[198:201], v[116:119]
	v_mfma_f32_16x16x32_bf16 v[72:75], v[132:135], v[174:177], v[72:75]
	v_mfma_f32_16x16x32_bf16 v[28:31], v[166:169], v[174:177], v[28:31]
	v_mfma_f32_16x16x32_bf16 v[64:67], v[132:135], v[182:185], v[64:67]
	v_mfma_f32_16x16x32_bf16 v[24:27], v[166:169], v[182:185], v[24:27]
	v_mfma_f32_16x16x32_bf16 v[128:131], v[132:135], v[194:197], v[128:131]
	v_mfma_f32_16x16x32_bf16 v[124:127], v[166:169], v[194:197], v[124:127]
	v_mfma_f32_16x16x32_bf16 v[120:123], v[132:135], v[202:205], v[120:123]
	v_mfma_f32_16x16x32_bf16 v[116:119], v[166:169], v[202:205], v[116:119]
	s_setprio 0
	s_barrier
	s_add_i32 s8, s54, s43
	v_lshl_add_u64 v[186:187], s[36:37], 0, v[138:139]
	s_mov_b32 m0, s8
	ds_read_b128 v[206:209], v160
	ds_read_b128 v[210:213], v160 offset:1024
	ds_read_b128 v[214:217], v160 offset:2048
	ds_read_b128 v[218:221], v160 offset:3072
	global_load_lds_dwordx4 v[186:187], off
	v_lshl_add_u64 v[222:223], s[36:37], 0, v[142:143]
	s_add_i32 m0, s8, 0x2000
	s_nop 0
	global_load_lds_dwordx4 v[222:223], off
	s_barrier
	s_waitcnt lgkmcnt(0)
	s_setprio 1
	s_waitcnt lgkmcnt(0)
	v_mfma_f32_16x16x32_bf16 v[56:59], v[206:209], v[170:173], v[56:59]
	v_mfma_f32_16x16x32_bf16 v[20:23], v[214:217], v[170:173], v[20:23]
	v_mfma_f32_16x16x32_bf16 v[52:55], v[206:209], v[178:181], v[52:55]
	v_mfma_f32_16x16x32_bf16 v[16:19], v[214:217], v[178:181], v[16:19]
	v_mfma_f32_16x16x32_bf16 v[112:115], v[206:209], v[190:193], v[112:115]
	v_mfma_f32_16x16x32_bf16 v[108:111], v[214:217], v[190:193], v[108:111]
	v_mfma_f32_16x16x32_bf16 v[104:107], v[206:209], v[198:201], v[104:107]
	v_mfma_f32_16x16x32_bf16 v[100:103], v[214:217], v[198:201], v[100:103]
	v_mfma_f32_16x16x32_bf16 v[56:59], v[210:213], v[174:177], v[56:59]
	v_mfma_f32_16x16x32_bf16 v[20:23], v[218:221], v[174:177], v[20:23]
	v_mfma_f32_16x16x32_bf16 v[52:55], v[210:213], v[182:185], v[52:55]
	v_mfma_f32_16x16x32_bf16 v[16:19], v[218:221], v[182:185], v[16:19]
	v_mfma_f32_16x16x32_bf16 v[112:115], v[210:213], v[194:197], v[112:115]
	v_mfma_f32_16x16x32_bf16 v[108:111], v[218:221], v[194:197], v[108:111]
	v_mfma_f32_16x16x32_bf16 v[104:107], v[210:213], v[202:205], v[104:107]
	v_mfma_f32_16x16x32_bf16 v[100:103], v[218:221], v[202:205], v[100:103]
	s_setprio 0
	s_mov_b32 m0, s44
	v_lshl_add_u64 v[224:225], s[38:39], 0, v[136:137]
	s_barrier
	ds_read_b128 v[170:173], v159 offset:16384
	ds_read_b128 v[174:177], v159 offset:17408
	ds_read_b128 v[178:181], v159 offset:18432
	ds_read_b128 v[182:185], v159 offset:19456
	ds_read_b128 v[190:193], v159 offset:20480
	ds_read_b128 v[194:197], v159 offset:21504
	ds_read_b128 v[198:201], v159 offset:22528
	ds_read_b128 v[202:205], v159 offset:23552
	global_load_lds_dwordx4 v[224:225], off
	v_lshl_add_u64 v[226:227], s[38:39], 0, v[140:141]
	s_mov_b32 m0, s45
	s_nop 0
	global_load_lds_dwordx4 v[226:227], off
	s_barrier
	s_waitcnt lgkmcnt(0)
	s_setprio 1
	s_waitcnt lgkmcnt(0)
	v_mfma_f32_16x16x32_bf16 v[44:47], v[48:51], v[170:173], v[44:47]
	v_mfma_f32_16x16x32_bf16 v[12:15], v[162:165], v[170:173], v[12:15]
	v_mfma_f32_16x16x32_bf16 v[40:43], v[48:51], v[178:181], v[40:43]
	v_mfma_f32_16x16x32_bf16 v[8:11], v[162:165], v[178:181], v[8:11]
	v_mfma_f32_16x16x32_bf16 v[96:99], v[48:51], v[190:193], v[96:99]
	v_mfma_f32_16x16x32_bf16 v[92:95], v[162:165], v[190:193], v[92:95]
	v_mfma_f32_16x16x32_bf16 v[76:79], v[162:165], v[198:201], v[76:79]
	v_mfma_f32_16x16x32_bf16 v[44:47], v[132:135], v[174:177], v[44:47]
	v_mfma_f32_16x16x32_bf16 v[12:15], v[166:169], v[174:177], v[12:15]
	v_mfma_f32_16x16x32_bf16 v[40:43], v[132:135], v[182:185], v[40:43]
	v_mfma_f32_16x16x32_bf16 v[8:11], v[166:169], v[182:185], v[8:11]
	v_mfma_f32_16x16x32_bf16 v[96:99], v[132:135], v[194:197], v[96:99]
	v_mfma_f32_16x16x32_bf16 v[92:95], v[166:169], v[194:197], v[92:95]
	v_mfma_f32_16x16x32_bf16 v[48:51], v[48:51], v[198:201], v[84:87]
	v_mfma_f32_16x16x32_bf16 v[76:79], v[166:169], v[202:205], v[76:79]
	v_mfma_f32_16x16x32_bf16 v[48:51], v[132:135], v[202:205], v[48:51]
	s_setprio 0
	s_barrier
	s_add_u32 s8, s36, 0x40000
	s_addc_u32 s9, s37, 0
	s_add_i32 s71, s55, s43
	v_lshl_add_u64 v[84:85], s[8:9], 0, v[138:139]
	s_mov_b32 m0, s71
	s_nop 0
	global_load_lds_dwordx4 v[84:85], off
	v_lshl_add_u64 v[84:85], s[8:9], 0, v[142:143]
	s_add_i32 m0, s71, 0x2000
	s_nop 0
	global_load_lds_dwordx4 v[84:85], off
	s_waitcnt vmcnt(6)
	s_barrier
	s_setprio 1
	v_mfma_f32_16x16x32_bf16 v[36:39], v[206:209], v[170:173], v[36:39]
	v_mfma_f32_16x16x32_bf16 v[4:7], v[214:217], v[170:173], v[4:7]
	v_mfma_f32_16x16x32_bf16 v[32:35], v[206:209], v[178:181], v[32:35]
	v_mfma_f32_16x16x32_bf16 v[0:3], v[214:217], v[178:181], v[0:3]
	v_mfma_f32_16x16x32_bf16 v[84:87], v[206:209], v[190:193], v[88:91]
	v_mfma_f32_16x16x32_bf16 v[80:83], v[214:217], v[190:193], v[80:83]
	v_mfma_f32_16x16x32_bf16 v[68:71], v[206:209], v[198:201], v[68:71]
	v_mfma_f32_16x16x32_bf16 v[60:63], v[214:217], v[198:201], v[60:63]
	v_mfma_f32_16x16x32_bf16 v[36:39], v[210:213], v[174:177], v[36:39]
	v_mfma_f32_16x16x32_bf16 v[4:7], v[218:221], v[174:177], v[4:7]
	v_mfma_f32_16x16x32_bf16 v[32:35], v[210:213], v[182:185], v[32:35]
	v_mfma_f32_16x16x32_bf16 v[0:3], v[218:221], v[182:185], v[0:3]
	v_mfma_f32_16x16x32_bf16 v[88:91], v[210:213], v[194:197], v[84:87]
	v_mfma_f32_16x16x32_bf16 v[80:83], v[218:221], v[194:197], v[80:83]
	v_mfma_f32_16x16x32_bf16 v[68:71], v[210:213], v[202:205], v[68:71]
	v_mfma_f32_16x16x32_bf16 v[60:63], v[218:221], v[202:205], v[60:63]
	s_setprio 0
	s_add_i32 s71, 0, 0x18000
	v_add_u32_e32 v166, s71, v156
	s_barrier
	ds_read_b128 v[84:87], v166
	ds_read_b128 v[132:135], v166 offset:1024
	ds_read_b128 v[162:165], v166 offset:2048
	ds_read_b128 v[166:169], v166 offset:3072
	s_add_u32 s8, s38, 0x40000
	s_addc_u32 s9, s39, 0
	s_mov_b32 m0, s46
	v_lshl_add_u64 v[206:207], s[8:9], 0, v[136:137]
	ds_read_b128 v[170:173], v159 offset:32768
	ds_read_b128 v[174:177], v159 offset:33792
	ds_read_b128 v[178:181], v159 offset:34816
	ds_read_b128 v[182:185], v159 offset:35840
	ds_read_b128 v[190:193], v159 offset:36864
	ds_read_b128 v[194:197], v159 offset:37888
	ds_read_b128 v[198:201], v159 offset:38912
	ds_read_b128 v[202:205], v159 offset:39936
	global_load_lds_dwordx4 v[206:207], off
	v_lshl_add_u64 v[206:207], s[8:9], 0, v[140:141]
	s_mov_b32 m0, s47
	s_nop 0
	global_load_lds_dwordx4 v[206:207], off
	s_waitcnt lgkmcnt(8)
	s_barrier
	s_waitcnt lgkmcnt(0)
	s_setprio 1
	s_waitcnt lgkmcnt(0)
	v_mfma_f32_16x16x32_bf16 v[72:75], v[84:87], v[170:173], v[72:75]
	v_mfma_f32_16x16x32_bf16 v[28:31], v[162:165], v[170:173], v[28:31]
	v_mfma_f32_16x16x32_bf16 v[64:67], v[84:87], v[178:181], v[64:67]
	v_mfma_f32_16x16x32_bf16 v[24:27], v[162:165], v[178:181], v[24:27]
	v_mfma_f32_16x16x32_bf16 v[128:131], v[84:87], v[190:193], v[128:131]
	v_mfma_f32_16x16x32_bf16 v[124:127], v[162:165], v[190:193], v[124:127]
	v_mfma_f32_16x16x32_bf16 v[120:123], v[84:87], v[198:201], v[120:123]
	v_mfma_f32_16x16x32_bf16 v[116:119], v[162:165], v[198:201], v[116:119]
	v_mfma_f32_16x16x32_bf16 v[72:75], v[132:135], v[174:177], v[72:75]
	v_mfma_f32_16x16x32_bf16 v[28:31], v[166:169], v[174:177], v[28:31]
	v_mfma_f32_16x16x32_bf16 v[64:67], v[132:135], v[182:185], v[64:67]
	v_mfma_f32_16x16x32_bf16 v[24:27], v[166:169], v[182:185], v[24:27]
	v_mfma_f32_16x16x32_bf16 v[128:131], v[132:135], v[194:197], v[128:131]
	v_mfma_f32_16x16x32_bf16 v[124:127], v[166:169], v[194:197], v[124:127]
	v_mfma_f32_16x16x32_bf16 v[120:123], v[132:135], v[202:205], v[120:123]
	v_mfma_f32_16x16x32_bf16 v[116:119], v[166:169], v[202:205], v[116:119]
	s_setprio 0
	s_barrier
	s_add_i32 s38, 0, 0x1c000
	s_add_i32 s8, s71, s43
	v_add_u32_e32 v189, s38, v156
	v_lshl_add_u64 v[186:187], v[186:187], 0, s[24:25]
	s_mov_b32 m0, s8
	ds_read_b128 v[206:209], v189
	ds_read_b128 v[210:213], v189 offset:1024
	ds_read_b128 v[214:217], v189 offset:2048
	ds_read_b128 v[218:221], v189 offset:3072
	global_load_lds_dwordx4 v[186:187], off
	v_lshl_add_u64 v[186:187], v[222:223], 0, s[24:25]
	s_add_i32 m0, s8, 0x2000
	s_nop 0
	global_load_lds_dwordx4 v[186:187], off
	s_barrier
	s_waitcnt lgkmcnt(0)
	s_setprio 1
	s_waitcnt lgkmcnt(0)
	v_mfma_f32_16x16x32_bf16 v[56:59], v[206:209], v[170:173], v[56:59]
	v_mfma_f32_16x16x32_bf16 v[20:23], v[214:217], v[170:173], v[20:23]
	v_mfma_f32_16x16x32_bf16 v[52:55], v[206:209], v[178:181], v[52:55]
	v_mfma_f32_16x16x32_bf16 v[16:19], v[214:217], v[178:181], v[16:19]
	v_mfma_f32_16x16x32_bf16 v[112:115], v[206:209], v[190:193], v[112:115]
	v_mfma_f32_16x16x32_bf16 v[108:111], v[214:217], v[190:193], v[108:111]
	v_mfma_f32_16x16x32_bf16 v[104:107], v[206:209], v[198:201], v[104:107]
	v_mfma_f32_16x16x32_bf16 v[100:103], v[214:217], v[198:201], v[100:103]
	v_mfma_f32_16x16x32_bf16 v[56:59], v[210:213], v[174:177], v[56:59]
	v_mfma_f32_16x16x32_bf16 v[20:23], v[218:221], v[174:177], v[20:23]
	v_mfma_f32_16x16x32_bf16 v[52:55], v[210:213], v[182:185], v[52:55]
	v_mfma_f32_16x16x32_bf16 v[16:19], v[218:221], v[182:185], v[16:19]
	v_mfma_f32_16x16x32_bf16 v[112:115], v[210:213], v[194:197], v[112:115]
	v_mfma_f32_16x16x32_bf16 v[108:111], v[218:221], v[194:197], v[108:111]
	v_mfma_f32_16x16x32_bf16 v[104:107], v[210:213], v[202:205], v[104:107]
	v_mfma_f32_16x16x32_bf16 v[100:103], v[218:221], v[202:205], v[100:103]
	s_setprio 0
	s_mov_b32 m0, s50
	v_lshl_add_u64 v[186:187], v[224:225], 0, s[24:25]
	s_barrier
	ds_read_b128 v[170:173], v159 offset:49152
	ds_read_b128 v[174:177], v159 offset:50176
	ds_read_b128 v[178:181], v159 offset:51200
	ds_read_b128 v[182:185], v159 offset:52224
	ds_read_b128 v[190:193], v159 offset:53248
	ds_read_b128 v[194:197], v159 offset:54272
	ds_read_b128 v[198:201], v159 offset:55296
	ds_read_b128 v[202:205], v159 offset:56320
	global_load_lds_dwordx4 v[186:187], off
	v_lshl_add_u64 v[186:187], v[226:227], 0, s[24:25]
	s_mov_b32 m0, s51
	s_nop 0
	global_load_lds_dwordx4 v[186:187], off
	s_barrier
	s_waitcnt lgkmcnt(0)
	s_setprio 1
	s_waitcnt lgkmcnt(0)
	v_mfma_f32_16x16x32_bf16 v[48:51], v[84:87], v[198:201], v[48:51]
	v_mfma_f32_16x16x32_bf16 v[44:47], v[84:87], v[170:173], v[44:47]
	v_mfma_f32_16x16x32_bf16 v[12:15], v[162:165], v[170:173], v[12:15]
	v_mfma_f32_16x16x32_bf16 v[40:43], v[84:87], v[178:181], v[40:43]
	v_mfma_f32_16x16x32_bf16 v[8:11], v[162:165], v[178:181], v[8:11]
	v_mfma_f32_16x16x32_bf16 v[96:99], v[84:87], v[190:193], v[96:99]
	v_mfma_f32_16x16x32_bf16 v[92:95], v[162:165], v[190:193], v[92:95]
	v_mfma_f32_16x16x32_bf16 v[84:87], v[132:135], v[202:205], v[48:51]
	v_mfma_f32_16x16x32_bf16 v[48:51], v[162:165], v[198:201], v[76:79]
	v_mfma_f32_16x16x32_bf16 v[44:47], v[132:135], v[174:177], v[44:47]
	v_mfma_f32_16x16x32_bf16 v[12:15], v[166:169], v[174:177], v[12:15]
	v_mfma_f32_16x16x32_bf16 v[40:43], v[132:135], v[182:185], v[40:43]
	v_mfma_f32_16x16x32_bf16 v[8:11], v[166:169], v[182:185], v[8:11]
	v_mfma_f32_16x16x32_bf16 v[96:99], v[132:135], v[194:197], v[96:99]
	v_mfma_f32_16x16x32_bf16 v[92:95], v[166:169], v[194:197], v[92:95]
	v_mfma_f32_16x16x32_bf16 v[76:79], v[166:169], v[202:205], v[48:51]
	s_setprio 0
	s_barrier
	s_add_u32 s8, s36, 0x40080
	s_addc_u32 s9, s37, 0
	s_add_i32 s36, s38, s43
	v_lshl_add_u64 v[48:49], s[8:9], 0, v[138:139]
	s_mov_b32 m0, s36
	s_nop 0
	global_load_lds_dwordx4 v[48:49], off
	v_lshl_add_u64 v[48:49], s[8:9], 0, v[142:143]
	s_add_i32 m0, s36, 0x2000
	s_nop 0
	global_load_lds_dwordx4 v[48:49], off
	s_waitcnt vmcnt(6)
	s_barrier
	s_setprio 1
	v_mfma_f32_16x16x32_bf16 v[48:51], v[206:209], v[190:193], v[88:91]
	v_mfma_f32_16x16x32_bf16 v[88:91], v[210:213], v[194:197], v[48:51]
	v_mfma_f32_16x16x32_bf16 v[48:51], v[214:217], v[190:193], v[80:83]
	v_mfma_f32_16x16x32_bf16 v[80:83], v[218:221], v[194:197], v[48:51]
	v_mfma_f32_16x16x32_bf16 v[48:51], v[206:209], v[198:201], v[68:71]
	v_mfma_f32_16x16x32_bf16 v[36:39], v[206:209], v[170:173], v[36:39]
	v_mfma_f32_16x16x32_bf16 v[4:7], v[214:217], v[170:173], v[4:7]
	v_mfma_f32_16x16x32_bf16 v[32:35], v[206:209], v[178:181], v[32:35]
	v_mfma_f32_16x16x32_bf16 v[0:3], v[214:217], v[178:181], v[0:3]
	v_mfma_f32_16x16x32_bf16 v[68:71], v[210:213], v[202:205], v[48:51]
	v_mfma_f32_16x16x32_bf16 v[48:51], v[214:217], v[198:201], v[60:63]
	v_mfma_f32_16x16x32_bf16 v[36:39], v[210:213], v[174:177], v[36:39]
	v_mfma_f32_16x16x32_bf16 v[4:7], v[218:221], v[174:177], v[4:7]
	v_mfma_f32_16x16x32_bf16 v[32:35], v[210:213], v[182:185], v[32:35]
	v_mfma_f32_16x16x32_bf16 v[0:3], v[218:221], v[182:185], v[0:3]
	v_mfma_f32_16x16x32_bf16 v[60:63], v[218:221], v[202:205], v[48:51]
	s_setprio 0
	s_add_i32 s70, s70, 2
	s_add_u32 s68, s68, 0x100
	s_addc_u32 s69, s69, 0
	s_cmp_gt_u32 s70, 13
	s_mov_b64 s[8:9], s[34:35]
	s_barrier
	s_cbranch_scc0 .LBB0_191
	v_cndmask_b32_e64 v48, 0, 1, s[30:31]
	v_cmp_ne_u32_e64 s[8:9], 1, v48
	s_andn2_b64 vcc, exec, s[30:31]
	s_cbranch_vccnz .LBB0_196
	v_mov_b32_e32 v48, 0
	v_mov_b32_e32 v49, 0
	v_mov_b32_e32 v50, 0
	v_mov_b32_e32 v51, 0
	s_and_saveexec_b64 s[30:31], s[2:3]
	s_cbranch_execz .LBB0_195
	s_lshl_b32 s34, s14, 7
	s_ashr_i32 s35, s34, 31
	v_lshl_add_u64 v[48:49], s[34:35], 2, v[148:149]
	global_load_dwordx4 v[48:51], v[48:49], off

.LBB0_452:
	ds_read_b128 v[16:19], v212
	ds_read_b128 v[20:23], v212 offset:1024
	ds_read_b128 v[24:27], v212 offset:2048
	ds_read_b128 v[68:71], v212 offset:3072
	s_add_u32 s34, s8, 0x100
	s_addc_u32 s35, s9, 0
	s_cmp_eq_u32 s71, 12
	s_cselect_b32 s39, s63, s35
	s_cselect_b32 s38, s67, s34
	s_cselect_b32 s37, s11, s70
	s_cselect_b32 s36, s68, s69
	v_lshl_add_u64 v[176:177], s[8:9], 0, v[204:205]
	s_add_i32 m0, s46, 0xc000
	ds_read_b128 v[96:99], v213
	ds_read_b128 v[148:151], v213 offset:1024
	ds_read_b128 v[152:155], v213 offset:2048
	ds_read_b128 v[156:159], v213 offset:3072
	ds_read_b128 v[160:163], v213 offset:4096
	ds_read_b128 v[164:167], v213 offset:5120
	ds_read_b128 v[168:171], v213 offset:6144
	ds_read_b128 v[172:175], v213 offset:7168
	global_load_lds_dwordx4 v[176:177], off
	v_lshl_add_u64 v[176:177], s[8:9], 0, v[206:207]
	s_add_i32 m0, s46, 0xe000
	s_nop 0
	global_load_lds_dwordx4 v[176:177], off
	s_waitcnt lgkmcnt(8)
	s_barrier
	s_waitcnt lgkmcnt(0)
	s_setprio 1
	s_waitcnt lgkmcnt(0)
	v_mfma_f32_16x16x32_bf16 v[112:115], v[16:19], v[96:99], v[112:115]
	v_mfma_f32_16x16x32_bf16 v[40:43], v[24:27], v[96:99], v[40:43]
	v_mfma_f32_16x16x32_bf16 v[108:111], v[16:19], v[152:155], v[108:111]
	v_mfma_f32_16x16x32_bf16 v[36:39], v[24:27], v[152:155], v[36:39]
	v_mfma_f32_16x16x32_bf16 v[144:147], v[16:19], v[160:163], v[144:147]
	v_mfma_f32_16x16x32_bf16 v[140:143], v[24:27], v[160:163], v[140:143]
	v_mfma_f32_16x16x32_bf16 v[136:139], v[16:19], v[168:171], v[136:139]
	v_mfma_f32_16x16x32_bf16 v[132:135], v[24:27], v[168:171], v[132:135]
	v_mfma_f32_16x16x32_bf16 v[112:115], v[20:23], v[148:151], v[112:115]
	v_mfma_f32_16x16x32_bf16 v[40:43], v[68:71], v[148:151], v[40:43]
	v_mfma_f32_16x16x32_bf16 v[108:111], v[20:23], v[156:159], v[108:111]
	v_mfma_f32_16x16x32_bf16 v[36:39], v[68:71], v[156:159], v[36:39]
	v_mfma_f32_16x16x32_bf16 v[144:147], v[20:23], v[164:167], v[144:147]
	v_mfma_f32_16x16x32_bf16 v[140:143], v[68:71], v[164:167], v[140:143]
	v_mfma_f32_16x16x32_bf16 v[136:139], v[20:23], v[172:175], v[136:139]
	v_mfma_f32_16x16x32_bf16 v[132:135], v[68:71], v[172:175], v[132:135]
	s_setprio 0
	s_barrier
	s_add_i32 s8, s56, s45
	v_lshl_add_u64 v[222:223], s[36:37], 0, v[192:193]
	s_mov_b32 m0, s8
	ds_read_b128 v[176:179], v214
	ds_read_b128 v[180:183], v214 offset:1024
	ds_read_b128 v[184:187], v214 offset:2048
	ds_read_b128 v[218:221], v214 offset:3072
	global_load_lds_dwordx4 v[222:223], off
	v_lshl_add_u64 v[224:225], s[36:37], 0, v[198:199]
	s_add_i32 m0, s8, 0x2000
	s_nop 0
	global_load_lds_dwordx4 v[224:225], off
	s_barrier
	s_waitcnt lgkmcnt(0)
	s_setprio 1
	s_waitcnt lgkmcnt(0)
	v_mfma_f32_16x16x32_bf16 v[104:107], v[176:179], v[96:99], v[104:107]
	v_mfma_f32_16x16x32_bf16 v[32:35], v[184:187], v[96:99], v[32:35]
	v_mfma_f32_16x16x32_bf16 v[28:31], v[184:187], v[152:155], v[28:31]
	v_mfma_f32_16x16x32_bf16 v[80:83], v[176:179], v[160:163], v[80:83]
	v_mfma_f32_16x16x32_bf16 v[92:95], v[184:187], v[160:163], v[92:95]
	v_mfma_f32_16x16x32_bf16 v[84:87], v[176:179], v[168:171], v[84:87]
	v_mfma_f32_16x16x32_bf16 v[88:91], v[184:187], v[168:171], v[88:91]
	v_mfma_f32_16x16x32_bf16 v[104:107], v[180:183], v[148:151], v[104:107]
	v_mfma_f32_16x16x32_bf16 v[32:35], v[218:221], v[148:151], v[32:35]
	v_mfma_f32_16x16x32_bf16 v[96:99], v[176:179], v[152:155], v[100:103]
	v_mfma_f32_16x16x32_bf16 v[28:31], v[218:221], v[156:159], v[28:31]
	v_mfma_f32_16x16x32_bf16 v[80:83], v[180:183], v[164:167], v[80:83]
	v_mfma_f32_16x16x32_bf16 v[92:95], v[218:221], v[164:167], v[92:95]
	v_mfma_f32_16x16x32_bf16 v[84:87], v[180:183], v[172:175], v[84:87]
	v_mfma_f32_16x16x32_bf16 v[88:91], v[218:221], v[172:175], v[88:91]
	v_mfma_f32_16x16x32_bf16 v[96:99], v[180:183], v[156:159], v[96:99]
	s_setprio 0
	s_mov_b32 m0, s46
	v_lshl_add_u64 v[226:227], s[38:39], 0, v[194:195]
	s_barrier
	ds_read_b128 v[100:103], v213 offset:16384
	ds_read_b128 v[148:151], v213 offset:17408
	ds_read_b128 v[152:155], v213 offset:18432
	ds_read_b128 v[156:159], v213 offset:19456
	ds_read_b128 v[160:163], v213 offset:20480
	ds_read_b128 v[164:167], v213 offset:21504
	ds_read_b128 v[168:171], v213 offset:22528
	ds_read_b128 v[172:175], v213 offset:23552
	global_load_lds_dwordx4 v[226:227], off
	v_lshl_add_u64 v[228:229], s[38:39], 0, v[196:197]
	s_mov_b32 m0, s47
	s_nop 0
	global_load_lds_dwordx4 v[228:229], off
	s_barrier
	s_waitcnt lgkmcnt(0)
	s_setprio 1
	s_waitcnt lgkmcnt(0)
	v_mfma_f32_16x16x32_bf16 v[76:79], v[16:19], v[100:103], v[76:79]
	v_mfma_f32_16x16x32_bf16 v[12:15], v[24:27], v[100:103], v[12:15]
	v_mfma_f32_16x16x32_bf16 v[72:75], v[16:19], v[152:155], v[72:75]
	v_mfma_f32_16x16x32_bf16 v[8:11], v[24:27], v[152:155], v[8:11]
	v_mfma_f32_16x16x32_bf16 v[128:131], v[16:19], v[160:163], v[128:131]
	v_mfma_f32_16x16x32_bf16 v[124:127], v[24:27], v[160:163], v[124:127]
	v_mfma_f32_16x16x32_bf16 v[16:19], v[16:19], v[168:171], v[120:123]
	v_mfma_f32_16x16x32_bf16 v[76:79], v[20:23], v[148:151], v[76:79]
	v_mfma_f32_16x16x32_bf16 v[12:15], v[68:71], v[148:151], v[12:15]
	v_mfma_f32_16x16x32_bf16 v[72:75], v[20:23], v[156:159], v[72:75]
	v_mfma_f32_16x16x32_bf16 v[8:11], v[68:71], v[156:159], v[8:11]
	v_mfma_f32_16x16x32_bf16 v[128:131], v[20:23], v[164:167], v[128:131]
	v_mfma_f32_16x16x32_bf16 v[124:127], v[68:71], v[164:167], v[124:127]
	v_mfma_f32_16x16x32_bf16 v[16:19], v[20:23], v[172:175], v[16:19]
	v_mfma_f32_16x16x32_bf16 v[20:23], v[24:27], v[168:171], v[116:119]
	v_mfma_f32_16x16x32_bf16 v[20:23], v[68:71], v[172:175], v[20:23]
	s_setprio 0
	s_barrier
	s_add_u32 s8, s36, 0x40000
	s_addc_u32 s9, s37, 0
	s_add_i32 s78, s57, s45
	v_lshl_add_u64 v[24:25], s[8:9], 0, v[192:193]
	s_mov_b32 m0, s78
	s_nop 0
	global_load_lds_dwordx4 v[24:25], off
	v_lshl_add_u64 v[24:25], s[8:9], 0, v[198:199]
	s_add_i32 m0, s78, 0x2000
	s_nop 0
	global_load_lds_dwordx4 v[24:25], off
	s_waitcnt vmcnt(6)
	s_barrier
	s_setprio 1
	v_mfma_f32_16x16x32_bf16 v[4:7], v[184:187], v[100:103], v[4:7]
	v_mfma_f32_16x16x32_bf16 v[60:63], v[176:179], v[152:155], v[60:63]
	v_mfma_f32_16x16x32_bf16 v[0:3], v[184:187], v[152:155], v[0:3]
	v_mfma_f32_16x16x32_bf16 v[44:47], v[176:179], v[160:163], v[44:47]
	v_mfma_f32_16x16x32_bf16 v[48:51], v[184:187], v[160:163], v[48:51]
	v_mfma_f32_16x16x32_bf16 v[52:55], v[176:179], v[168:171], v[52:55]
	v_mfma_f32_16x16x32_bf16 v[56:59], v[184:187], v[168:171], v[56:59]
	v_mfma_f32_16x16x32_bf16 v[24:27], v[176:179], v[100:103], v[64:67]
	v_mfma_f32_16x16x32_bf16 v[4:7], v[218:221], v[148:151], v[4:7]
	v_mfma_f32_16x16x32_bf16 v[60:63], v[180:183], v[156:159], v[60:63]
	v_mfma_f32_16x16x32_bf16 v[0:3], v[218:221], v[156:159], v[0:3]
	v_mfma_f32_16x16x32_bf16 v[44:47], v[180:183], v[164:167], v[44:47]
	v_mfma_f32_16x16x32_bf16 v[48:51], v[218:221], v[164:167], v[48:51]
	v_mfma_f32_16x16x32_bf16 v[52:55], v[180:183], v[172:175], v[52:55]
	v_mfma_f32_16x16x32_bf16 v[56:59], v[218:221], v[172:175], v[56:59]
	v_mfma_f32_16x16x32_bf16 v[24:27], v[180:183], v[148:151], v[24:27]
	s_setprio 0
	s_add_i32 s78, 0, 0x18000
	v_add_u32_e32 v100, s78, v208
	s_barrier
	ds_read_b128 v[64:67], v100
	ds_read_b128 v[68:71], v100 offset:1024
	ds_read_b128 v[116:119], v100 offset:2048
	ds_read_b128 v[148:151], v100 offset:3072
	s_add_u32 s8, s38, 0x40000
	s_addc_u32 s9, s39, 0
	s_mov_b32 m0, s48
	v_lshl_add_u64 v[176:177], s[8:9], 0, v[194:195]
	ds_read_b128 v[100:103], v213 offset:32768
	ds_read_b128 v[120:123], v213 offset:33792
	ds_read_b128 v[152:155], v213 offset:34816
	ds_read_b128 v[156:159], v213 offset:35840
	ds_read_b128 v[160:163], v213 offset:36864
	ds_read_b128 v[164:167], v213 offset:37888
	ds_read_b128 v[168:171], v213 offset:38912
	ds_read_b128 v[172:175], v213 offset:39936
	global_load_lds_dwordx4 v[176:177], off
	v_lshl_add_u64 v[176:177], s[8:9], 0, v[196:197]
	s_mov_b32 m0, s49
	s_nop 0
	global_load_lds_dwordx4 v[176:177], off
	s_waitcnt lgkmcnt(8)
	s_barrier
	s_waitcnt lgkmcnt(0)
	s_setprio 1
	s_waitcnt lgkmcnt(0)
	v_mfma_f32_16x16x32_bf16 v[112:115], v[64:67], v[100:103], v[112:115]
	v_mfma_f32_16x16x32_bf16 v[40:43], v[116:119], v[100:103], v[40:43]
	v_mfma_f32_16x16x32_bf16 v[108:111], v[64:67], v[152:155], v[108:111]
	v_mfma_f32_16x16x32_bf16 v[36:39], v[116:119], v[152:155], v[36:39]
	v_mfma_f32_16x16x32_bf16 v[144:147], v[64:67], v[160:163], v[144:147]
	v_mfma_f32_16x16x32_bf16 v[140:143], v[116:119], v[160:163], v[140:143]
	v_mfma_f32_16x16x32_bf16 v[136:139], v[64:67], v[168:171], v[136:139]
	v_mfma_f32_16x16x32_bf16 v[132:135], v[116:119], v[168:171], v[132:135]
	v_mfma_f32_16x16x32_bf16 v[112:115], v[68:71], v[120:123], v[112:115]
	v_mfma_f32_16x16x32_bf16 v[40:43], v[148:151], v[120:123], v[40:43]
	v_mfma_f32_16x16x32_bf16 v[108:111], v[68:71], v[156:159], v[108:111]
	v_mfma_f32_16x16x32_bf16 v[36:39], v[148:151], v[156:159], v[36:39]
	v_mfma_f32_16x16x32_bf16 v[144:147], v[68:71], v[164:167], v[144:147]
	v_mfma_f32_16x16x32_bf16 v[140:143], v[148:151], v[164:167], v[140:143]
	v_mfma_f32_16x16x32_bf16 v[136:139], v[68:71], v[172:175], v[136:139]
	v_mfma_f32_16x16x32_bf16 v[132:135], v[148:151], v[172:175], v[132:135]
	s_setprio 0
	s_barrier
	s_add_i32 s38, 0, 0x1c000
	s_add_i32 s8, s78, s45
	v_add_u32_e32 v217, s38, v208
	v_lshl_add_u64 v[222:223], v[222:223], 0, s[20:21]
	s_mov_b32 m0, s8
	ds_read_b128 v[176:179], v217
	ds_read_b128 v[180:183], v217 offset:1024
	ds_read_b128 v[184:187], v217 offset:2048
	ds_read_b128 v[218:221], v217 offset:3072
	global_load_lds_dwordx4 v[222:223], off
	v_lshl_add_u64 v[222:223], v[224:225], 0, s[20:21]
	s_add_i32 m0, s8, 0x2000
	s_nop 0
	global_load_lds_dwordx4 v[222:223], off
	s_barrier
	s_waitcnt lgkmcnt(0)
	s_setprio 1
	s_waitcnt lgkmcnt(0)
	v_mfma_f32_16x16x32_bf16 v[104:107], v[176:179], v[100:103], v[104:107]
	v_mfma_f32_16x16x32_bf16 v[32:35], v[184:187], v[100:103], v[32:35]
	v_mfma_f32_16x16x32_bf16 v[96:99], v[176:179], v[152:155], v[96:99]
	v_mfma_f32_16x16x32_bf16 v[28:31], v[184:187], v[152:155], v[28:31]
	v_mfma_f32_16x16x32_bf16 v[80:83], v[176:179], v[160:163], v[80:83]
	v_mfma_f32_16x16x32_bf16 v[92:95], v[184:187], v[160:163], v[92:95]
	v_mfma_f32_16x16x32_bf16 v[84:87], v[176:179], v[168:171], v[84:87]
	v_mfma_f32_16x16x32_bf16 v[88:91], v[184:187], v[168:171], v[88:91]
	v_mfma_f32_16x16x32_bf16 v[104:107], v[180:183], v[120:123], v[104:107]
	v_mfma_f32_16x16x32_bf16 v[32:35], v[218:221], v[120:123], v[32:35]
	v_mfma_f32_16x16x32_bf16 v[100:103], v[180:183], v[156:159], v[96:99]
	v_mfma_f32_16x16x32_bf16 v[28:31], v[218:221], v[156:159], v[28:31]
	v_mfma_f32_16x16x32_bf16 v[80:83], v[180:183], v[164:167], v[80:83]
	v_mfma_f32_16x16x32_bf16 v[92:95], v[218:221], v[164:167], v[92:95]
	v_mfma_f32_16x16x32_bf16 v[84:87], v[180:183], v[172:175], v[84:87]
	v_mfma_f32_16x16x32_bf16 v[88:91], v[218:221], v[172:175], v[88:91]
	s_setprio 0
	s_mov_b32 m0, s53
	v_lshl_add_u64 v[120:121], v[226:227], 0, s[20:21]
	s_barrier
	ds_read_b128 v[96:99], v213 offset:49152
	ds_read_b128 v[152:155], v213 offset:50176
	ds_read_b128 v[156:159], v213 offset:51200
	ds_read_b128 v[160:163], v213 offset:52224
	ds_read_b128 v[164:167], v213 offset:53248
	ds_read_b128 v[168:171], v213 offset:54272
	ds_read_b128 v[172:175], v213 offset:55296
	ds_read_b128 v[222:225], v213 offset:56320
	global_load_lds_dwordx4 v[120:121], off
	v_lshl_add_u64 v[120:121], v[228:229], 0, s[20:21]
	s_mov_b32 m0, s54
	s_nop 0
	global_load_lds_dwordx4 v[120:121], off
	s_barrier
	s_waitcnt lgkmcnt(0)
	s_setprio 1
	s_waitcnt lgkmcnt(0)
	v_mfma_f32_16x16x32_bf16 v[120:123], v[64:67], v[164:167], v[128:131]
	v_mfma_f32_16x16x32_bf16 v[128:131], v[68:71], v[168:171], v[120:123]
	v_mfma_f32_16x16x32_bf16 v[120:123], v[116:119], v[164:167], v[124:127]
	v_mfma_f32_16x16x32_bf16 v[16:19], v[64:67], v[172:175], v[16:19]
	v_mfma_f32_16x16x32_bf16 v[76:79], v[64:67], v[96:99], v[76:79]
	v_mfma_f32_16x16x32_bf16 v[12:15], v[116:119], v[96:99], v[12:15]
	v_mfma_f32_16x16x32_bf16 v[72:75], v[64:67], v[156:159], v[72:75]
	v_mfma_f32_16x16x32_bf16 v[8:11], v[116:119], v[156:159], v[8:11]
	v_mfma_f32_16x16x32_bf16 v[124:127], v[148:151], v[168:171], v[120:123]
	v_mfma_f32_16x16x32_bf16 v[120:123], v[68:71], v[222:225], v[16:19]
	v_mfma_f32_16x16x32_bf16 v[16:19], v[116:119], v[172:175], v[20:23]
	v_mfma_f32_16x16x32_bf16 v[76:79], v[68:71], v[152:155], v[76:79]
	v_mfma_f32_16x16x32_bf16 v[12:15], v[148:151], v[152:155], v[12:15]
	v_mfma_f32_16x16x32_bf16 v[72:75], v[68:71], v[160:163], v[72:75]
	v_mfma_f32_16x16x32_bf16 v[8:11], v[148:151], v[160:163], v[8:11]
	v_mfma_f32_16x16x32_bf16 v[116:119], v[148:151], v[222:225], v[16:19]
	s_setprio 0
	s_barrier
	s_add_u32 s8, s36, 0x40080
	s_addc_u32 s9, s37, 0
	s_add_i32 s36, s38, s45
	v_lshl_add_u64 v[16:17], s[8:9], 0, v[192:193]
	s_mov_b32 m0, s36
	s_nop 0
	global_load_lds_dwordx4 v[16:17], off
	v_lshl_add_u64 v[16:17], s[8:9], 0, v[198:199]
	s_add_i32 m0, s36, 0x2000
	s_nop 0
	global_load_lds_dwordx4 v[16:17], off
	s_waitcnt vmcnt(6)
	s_barrier
	s_setprio 1
	v_mfma_f32_16x16x32_bf16 v[16:19], v[176:179], v[96:99], v[24:27]
	v_mfma_f32_16x16x32_bf16 v[64:67], v[180:183], v[152:155], v[16:19]
	v_mfma_f32_16x16x32_bf16 v[16:19], v[176:179], v[156:159], v[60:63]
	v_mfma_f32_16x16x32_bf16 v[60:63], v[180:183], v[160:163], v[16:19]
	v_mfma_f32_16x16x32_bf16 v[16:19], v[176:179], v[164:167], v[44:47]
	v_mfma_f32_16x16x32_bf16 v[44:47], v[180:183], v[168:171], v[16:19]
	v_mfma_f32_16x16x32_bf16 v[16:19], v[184:187], v[164:167], v[48:51]
	v_mfma_f32_16x16x32_bf16 v[48:51], v[218:221], v[168:171], v[16:19]
	v_mfma_f32_16x16x32_bf16 v[16:19], v[176:179], v[172:175], v[52:55]
	v_mfma_f32_16x16x32_bf16 v[4:7], v[184:187], v[96:99], v[4:7]
	v_mfma_f32_16x16x32_bf16 v[0:3], v[184:187], v[156:159], v[0:3]
	v_mfma_f32_16x16x32_bf16 v[52:55], v[180:183], v[222:225], v[16:19]
	v_mfma_f32_16x16x32_bf16 v[16:19], v[184:187], v[172:175], v[56:59]
	v_mfma_f32_16x16x32_bf16 v[4:7], v[218:221], v[152:155], v[4:7]
	v_mfma_f32_16x16x32_bf16 v[0:3], v[218:221], v[160:163], v[0:3]
	v_mfma_f32_16x16x32_bf16 v[56:59], v[218:221], v[222:225], v[16:19]
	s_setprio 0
	s_add_i32 s71, s71, 2
	s_add_u32 s69, s69, 0x100
	s_addc_u32 s70, s70, 0
	s_cmp_gt_u32 s71, 13
	s_mov_b64 s[8:9], s[34:35]
	s_barrier
	s_cbranch_scc0 .LBB0_452
	v_cndmask_b32_e64 v16, 0, 1, s[30:31]
	v_cmp_ne_u32_e64 s[8:9], 1, v16
	s_andn2_b64 vcc, exec, s[30:31]
	s_cbranch_vccnz .LBB0_457
	v_mov_b32_e32 v16, 0
	v_mov_b32_e32 v17, 0
	v_mov_b32_e32 v18, 0
	v_mov_b32_e32 v19, 0
	s_and_saveexec_b64 s[30:31], s[2:3]
	s_cbranch_execz .LBB0_456
	s_lshl_b32 s34, s10, 7
	s_ashr_i32 s35, s34, 31
	v_lshl_add_u64 v[16:17], s[34:35], 2, v[202:203]
	global_load_dwordx4 v[16:19], v[16:17], off

.LBB0_642:
	ds_read_b128 v[24:27], v178
	ds_read_b128 v[28:31], v178 offset:1024
	ds_read_b128 v[160:163], v178 offset:2048
	ds_read_b128 v[164:167], v178 offset:3072
	s_add_u32 s38, s6, 0xfffc0080
	s_addc_u32 s39, s7, -1
	s_cmp_eq_u32 s68, 12
	s_cselect_b32 s41, s42, s39
	s_cselect_b32 s40, s43, s38
	s_cselect_b32 s39, s23, s67
	s_cselect_b32 s38, s44, s45
	v_lshl_add_u64 v[172:173], s[6:7], 0, v[152:153]
	s_add_i32 m0, s49, 0xc000
	ds_read_b128 v[168:171], v179
	ds_read_b128 v[182:185], v179 offset:1024
	ds_read_b128 v[190:193], v179 offset:2048
	ds_read_b128 v[194:197], v179 offset:3072
	ds_read_b128 v[198:201], v179 offset:4096
	ds_read_b128 v[202:205], v179 offset:5120
	ds_read_b128 v[206:209], v179 offset:6144
	ds_read_b128 v[210:213], v179 offset:7168
	global_load_lds_dwordx4 v[172:173], off
	v_lshl_add_u64 v[172:173], s[6:7], 0, v[154:155]
	s_add_i32 m0, s49, 0xe000
	s_nop 0
	global_load_lds_dwordx4 v[172:173], off
	s_waitcnt lgkmcnt(8)
	s_barrier
	s_waitcnt lgkmcnt(0)
	s_setprio 1
	s_waitcnt lgkmcnt(0)
	v_mfma_f32_16x16x32_bf16 v[132:135], v[24:27], v[168:171], v[132:135]
	v_mfma_f32_16x16x32_bf16 v[128:131], v[160:163], v[168:171], v[128:131]
	v_mfma_f32_16x16x32_bf16 v[116:119], v[24:27], v[190:193], v[116:119]
	v_mfma_f32_16x16x32_bf16 v[112:115], v[160:163], v[190:193], v[112:115]
	v_mfma_f32_16x16x32_bf16 v[100:103], v[24:27], v[198:201], v[100:103]
	v_mfma_f32_16x16x32_bf16 v[96:99], v[160:163], v[198:201], v[96:99]
	v_mfma_f32_16x16x32_bf16 v[84:87], v[24:27], v[206:209], v[84:87]
	v_mfma_f32_16x16x32_bf16 v[80:83], v[160:163], v[206:209], v[80:83]
	v_mfma_f32_16x16x32_bf16 v[132:135], v[28:31], v[182:185], v[132:135]
	v_mfma_f32_16x16x32_bf16 v[128:131], v[164:167], v[182:185], v[128:131]
	v_mfma_f32_16x16x32_bf16 v[116:119], v[28:31], v[194:197], v[116:119]
	v_mfma_f32_16x16x32_bf16 v[112:115], v[164:167], v[194:197], v[112:115]
	v_mfma_f32_16x16x32_bf16 v[100:103], v[28:31], v[202:205], v[100:103]
	v_mfma_f32_16x16x32_bf16 v[96:99], v[164:167], v[202:205], v[96:99]
	v_mfma_f32_16x16x32_bf16 v[84:87], v[28:31], v[210:213], v[84:87]
	v_mfma_f32_16x16x32_bf16 v[80:83], v[164:167], v[210:213], v[80:83]
	s_setprio 0
	s_barrier
	s_add_i32 s69, s59, s48
	v_lshl_add_u64 v[172:173], s[38:39], 0, v[136:137]
	s_mov_b32 m0, s69
	ds_read_b128 v[214:217], v180
	ds_read_b128 v[218:221], v180 offset:1024
	ds_read_b128 v[222:225], v180 offset:2048
	ds_read_b128 v[226:229], v180 offset:3072
	global_load_lds_dwordx4 v[172:173], off
	v_lshl_add_u64 v[186:187], s[38:39], 0, v[144:145]
	s_add_i32 m0, s69, 0x2000
	s_nop 0
	global_load_lds_dwordx4 v[186:187], off
	s_barrier
	s_waitcnt lgkmcnt(0)
	s_setprio 1
	s_waitcnt lgkmcnt(0)
	v_mfma_f32_16x16x32_bf16 v[124:127], v[214:217], v[168:171], v[124:127]
	v_mfma_f32_16x16x32_bf16 v[120:123], v[222:225], v[168:171], v[120:123]
	v_mfma_f32_16x16x32_bf16 v[108:111], v[214:217], v[190:193], v[108:111]
	v_mfma_f32_16x16x32_bf16 v[104:107], v[222:225], v[190:193], v[104:107]
	v_mfma_f32_16x16x32_bf16 v[92:95], v[214:217], v[198:201], v[92:95]
	v_mfma_f32_16x16x32_bf16 v[88:91], v[222:225], v[198:201], v[88:91]
	v_mfma_f32_16x16x32_bf16 v[76:79], v[214:217], v[206:209], v[76:79]
	v_mfma_f32_16x16x32_bf16 v[72:75], v[222:225], v[206:209], v[72:75]
	v_mfma_f32_16x16x32_bf16 v[124:127], v[218:221], v[182:185], v[124:127]
	v_mfma_f32_16x16x32_bf16 v[120:123], v[226:229], v[182:185], v[120:123]
	v_mfma_f32_16x16x32_bf16 v[108:111], v[218:221], v[194:197], v[108:111]
	v_mfma_f32_16x16x32_bf16 v[104:107], v[226:229], v[194:197], v[104:107]
	v_mfma_f32_16x16x32_bf16 v[92:95], v[218:221], v[202:205], v[92:95]
	v_mfma_f32_16x16x32_bf16 v[88:91], v[226:229], v[202:205], v[88:91]
	v_mfma_f32_16x16x32_bf16 v[76:79], v[218:221], v[210:213], v[76:79]
	v_mfma_f32_16x16x32_bf16 v[72:75], v[226:229], v[210:213], v[72:75]
	s_setprio 0
	s_mov_b32 m0, s49
	v_lshl_add_u64 v[230:231], s[40:41], 0, v[140:141]
	s_barrier
	ds_read_b128 v[168:171], v179 offset:16384
	ds_read_b128 v[182:185], v179 offset:17408
	ds_read_b128 v[190:193], v179 offset:18432
	ds_read_b128 v[194:197], v179 offset:19456
	ds_read_b128 v[198:201], v179 offset:20480
	ds_read_b128 v[202:205], v179 offset:21504
	ds_read_b128 v[206:209], v179 offset:22528
	ds_read_b128 v[210:213], v179 offset:23552
	global_load_lds_dwordx4 v[230:231], off
	v_lshl_add_u64 v[232:233], s[40:41], 0, v[142:143]
	s_mov_b32 m0, s50
	s_nop 0
	global_load_lds_dwordx4 v[232:233], off
	s_barrier
	s_waitcnt lgkmcnt(0)
	s_setprio 1
	s_waitcnt lgkmcnt(0)
	v_mfma_f32_16x16x32_bf16 v[68:71], v[24:27], v[168:171], v[68:71]
	v_mfma_f32_16x16x32_bf16 v[64:67], v[160:163], v[168:171], v[64:67]
	v_mfma_f32_16x16x32_bf16 v[52:55], v[24:27], v[190:193], v[52:55]
	v_mfma_f32_16x16x32_bf16 v[48:51], v[160:163], v[190:193], v[48:51]
	v_mfma_f32_16x16x32_bf16 v[36:39], v[24:27], v[198:201], v[36:39]
	v_mfma_f32_16x16x32_bf16 v[32:35], v[160:163], v[198:201], v[32:35]
	v_mfma_f32_16x16x32_bf16 v[12:15], v[24:27], v[206:209], v[12:15]
	v_mfma_f32_16x16x32_bf16 v[8:11], v[160:163], v[206:209], v[8:11]
	v_mfma_f32_16x16x32_bf16 v[68:71], v[28:31], v[182:185], v[68:71]
	v_mfma_f32_16x16x32_bf16 v[64:67], v[164:167], v[182:185], v[64:67]
	v_mfma_f32_16x16x32_bf16 v[52:55], v[28:31], v[194:197], v[52:55]
	v_mfma_f32_16x16x32_bf16 v[48:51], v[164:167], v[194:197], v[48:51]
	v_mfma_f32_16x16x32_bf16 v[36:39], v[28:31], v[202:205], v[36:39]
	v_mfma_f32_16x16x32_bf16 v[32:35], v[164:167], v[202:205], v[32:35]
	v_mfma_f32_16x16x32_bf16 v[12:15], v[28:31], v[210:213], v[12:15]
	v_mfma_f32_16x16x32_bf16 v[8:11], v[164:167], v[210:213], v[8:11]
	s_setprio 0
	s_barrier
	s_add_u32 s70, s38, 0x40000
	s_addc_u32 s71, s39, 0
	s_add_i32 s69, s60, s48
	v_lshl_add_u64 v[24:25], s[70:71], 0, v[136:137]
	s_mov_b32 m0, s69
	s_nop 0
	global_load_lds_dwordx4 v[24:25], off
	v_lshl_add_u64 v[24:25], s[70:71], 0, v[144:145]
	s_add_i32 m0, s69, 0x2000
	s_nop 0
	global_load_lds_dwordx4 v[24:25], off
	s_waitcnt vmcnt(6)
	s_barrier
	s_setprio 1
	v_mfma_f32_16x16x32_bf16 v[44:47], v[214:217], v[190:193], v[44:47]
	v_mfma_f32_16x16x32_bf16 v[40:43], v[222:225], v[190:193], v[40:43]
	v_mfma_f32_16x16x32_bf16 v[20:23], v[214:217], v[198:201], v[20:23]
	v_mfma_f32_16x16x32_bf16 v[16:19], v[222:225], v[198:201], v[16:19]
	v_mfma_f32_16x16x32_bf16 v[4:7], v[214:217], v[206:209], v[4:7]
	v_mfma_f32_16x16x32_bf16 v[0:3], v[222:225], v[206:209], v[0:3]
	v_mfma_f32_16x16x32_bf16 v[24:27], v[214:217], v[168:171], v[60:63]
	v_mfma_f32_16x16x32_bf16 v[28:31], v[222:225], v[168:171], v[56:59]
	v_mfma_f32_16x16x32_bf16 v[44:47], v[218:221], v[194:197], v[44:47]
	v_mfma_f32_16x16x32_bf16 v[40:43], v[226:229], v[194:197], v[40:43]
	v_mfma_f32_16x16x32_bf16 v[20:23], v[218:221], v[202:205], v[20:23]
	v_mfma_f32_16x16x32_bf16 v[16:19], v[226:229], v[202:205], v[16:19]
	v_mfma_f32_16x16x32_bf16 v[4:7], v[218:221], v[210:213], v[4:7]
	v_mfma_f32_16x16x32_bf16 v[0:3], v[226:229], v[210:213], v[0:3]
	v_mfma_f32_16x16x32_bf16 v[24:27], v[218:221], v[182:185], v[24:27]
	v_mfma_f32_16x16x32_bf16 v[28:31], v[226:229], v[182:185], v[28:31]
	s_setprio 0
	s_add_i32 s69, 0, 0x18000
	v_add_u32_e32 v138, s69, v175
	s_barrier
	ds_read_b128 v[56:59], v138
	ds_read_b128 v[60:63], v138 offset:1024
	ds_read_b128 v[160:163], v138 offset:2048
	ds_read_b128 v[164:167], v138 offset:3072
	s_add_u32 s40, s40, 0x40000
	s_addc_u32 s41, s41, 0
	s_mov_b32 m0, s51
	v_lshl_add_u64 v[214:215], s[40:41], 0, v[140:141]
	ds_read_b128 v[168:171], v179 offset:32768
	ds_read_b128 v[182:185], v179 offset:33792
	ds_read_b128 v[190:193], v179 offset:34816
	ds_read_b128 v[194:197], v179 offset:35840
	ds_read_b128 v[198:201], v179 offset:36864
	ds_read_b128 v[202:205], v179 offset:37888
	ds_read_b128 v[206:209], v179 offset:38912
	ds_read_b128 v[210:213], v179 offset:39936
	global_load_lds_dwordx4 v[214:215], off
	v_lshl_add_u64 v[214:215], s[40:41], 0, v[142:143]
	s_mov_b32 m0, s52
	s_nop 0
	global_load_lds_dwordx4 v[214:215], off
	s_waitcnt lgkmcnt(8)
	s_barrier
	s_waitcnt lgkmcnt(0)
	s_setprio 1
	s_waitcnt lgkmcnt(0)
	v_mfma_f32_16x16x32_bf16 v[132:135], v[56:59], v[168:171], v[132:135]
	v_mfma_f32_16x16x32_bf16 v[128:131], v[160:163], v[168:171], v[128:131]
	v_mfma_f32_16x16x32_bf16 v[116:119], v[56:59], v[190:193], v[116:119]
	v_mfma_f32_16x16x32_bf16 v[112:115], v[160:163], v[190:193], v[112:115]
	v_mfma_f32_16x16x32_bf16 v[100:103], v[56:59], v[198:201], v[100:103]
	v_mfma_f32_16x16x32_bf16 v[96:99], v[160:163], v[198:201], v[96:99]
	v_mfma_f32_16x16x32_bf16 v[84:87], v[56:59], v[206:209], v[84:87]
	v_mfma_f32_16x16x32_bf16 v[80:83], v[160:163], v[206:209], v[80:83]
	v_mfma_f32_16x16x32_bf16 v[132:135], v[60:63], v[182:185], v[132:135]
	v_mfma_f32_16x16x32_bf16 v[128:131], v[164:167], v[182:185], v[128:131]
	v_mfma_f32_16x16x32_bf16 v[116:119], v[60:63], v[194:197], v[116:119]
	v_mfma_f32_16x16x32_bf16 v[112:115], v[164:167], v[194:197], v[112:115]
	v_mfma_f32_16x16x32_bf16 v[100:103], v[60:63], v[202:205], v[100:103]
	v_mfma_f32_16x16x32_bf16 v[96:99], v[164:167], v[202:205], v[96:99]
	v_mfma_f32_16x16x32_bf16 v[84:87], v[60:63], v[210:213], v[84:87]
	v_mfma_f32_16x16x32_bf16 v[80:83], v[164:167], v[210:213], v[80:83]
	s_setprio 0
	s_barrier
	s_add_i32 s40, 0, 0x1c000
	s_add_i32 s41, s69, s48
	v_add_u32_e32 v138, s40, v175
	v_lshl_add_u64 v[172:173], v[172:173], 0, s[12:13]
	s_mov_b32 m0, s41
	ds_read_b128 v[214:217], v138
	ds_read_b128 v[218:221], v138 offset:1024
	ds_read_b128 v[222:225], v138 offset:2048
	ds_read_b128 v[226:229], v138 offset:3072
	global_load_lds_dwordx4 v[172:173], off
	v_lshl_add_u64 v[172:173], v[186:187], 0, s[12:13]
	s_add_i32 m0, s41, 0x2000
	s_nop 0
	global_load_lds_dwordx4 v[172:173], off
	s_barrier
	s_waitcnt lgkmcnt(0)
	s_setprio 1
	s_waitcnt lgkmcnt(0)
	v_mfma_f32_16x16x32_bf16 v[124:127], v[214:217], v[168:171], v[124:127]
	v_mfma_f32_16x16x32_bf16 v[120:123], v[222:225], v[168:171], v[120:123]
	v_mfma_f32_16x16x32_bf16 v[108:111], v[214:217], v[190:193], v[108:111]
	v_mfma_f32_16x16x32_bf16 v[104:107], v[222:225], v[190:193], v[104:107]
	v_mfma_f32_16x16x32_bf16 v[92:95], v[214:217], v[198:201], v[92:95]
	v_mfma_f32_16x16x32_bf16 v[88:91], v[222:225], v[198:201], v[88:91]
	v_mfma_f32_16x16x32_bf16 v[76:79], v[214:217], v[206:209], v[76:79]
	v_mfma_f32_16x16x32_bf16 v[72:75], v[222:225], v[206:209], v[72:75]
	v_mfma_f32_16x16x32_bf16 v[124:127], v[218:221], v[182:185], v[124:127]
	v_mfma_f32_16x16x32_bf16 v[120:123], v[226:229], v[182:185], v[120:123]
	v_mfma_f32_16x16x32_bf16 v[108:111], v[218:221], v[194:197], v[108:111]
	v_mfma_f32_16x16x32_bf16 v[104:107], v[226:229], v[194:197], v[104:107]
	v_mfma_f32_16x16x32_bf16 v[92:95], v[218:221], v[202:205], v[92:95]
	v_mfma_f32_16x16x32_bf16 v[88:91], v[226:229], v[202:205], v[88:91]
	v_mfma_f32_16x16x32_bf16 v[76:79], v[218:221], v[210:213], v[76:79]
	v_mfma_f32_16x16x32_bf16 v[72:75], v[226:229], v[210:213], v[72:75]
	s_setprio 0
	s_mov_b32 m0, s54
	v_lshl_add_u64 v[172:173], v[230:231], 0, s[12:13]
	s_barrier
	ds_read_b128 v[168:171], v179 offset:49152
	ds_read_b128 v[182:185], v179 offset:50176
	ds_read_b128 v[190:193], v179 offset:51200
	ds_read_b128 v[194:197], v179 offset:52224
	ds_read_b128 v[198:201], v179 offset:53248
	ds_read_b128 v[202:205], v179 offset:54272
	ds_read_b128 v[206:209], v179 offset:55296
	ds_read_b128 v[210:213], v179 offset:56320
	global_load_lds_dwordx4 v[172:173], off
	v_lshl_add_u64 v[172:173], v[232:233], 0, s[12:13]
	s_mov_b32 m0, s55
	s_nop 0
	global_load_lds_dwordx4 v[172:173], off
	s_barrier
	s_waitcnt lgkmcnt(0)
	s_setprio 1
	s_waitcnt lgkmcnt(0)
	v_mfma_f32_16x16x32_bf16 v[68:71], v[56:59], v[168:171], v[68:71]
	v_mfma_f32_16x16x32_bf16 v[64:67], v[160:163], v[168:171], v[64:67]
	v_mfma_f32_16x16x32_bf16 v[52:55], v[56:59], v[190:193], v[52:55]
	v_mfma_f32_16x16x32_bf16 v[48:51], v[160:163], v[190:193], v[48:51]
	v_mfma_f32_16x16x32_bf16 v[36:39], v[56:59], v[198:201], v[36:39]
	v_mfma_f32_16x16x32_bf16 v[32:35], v[160:163], v[198:201], v[32:35]
	v_mfma_f32_16x16x32_bf16 v[12:15], v[56:59], v[206:209], v[12:15]
	v_mfma_f32_16x16x32_bf16 v[8:11], v[160:163], v[206:209], v[8:11]
	v_mfma_f32_16x16x32_bf16 v[68:71], v[60:63], v[182:185], v[68:71]
	v_mfma_f32_16x16x32_bf16 v[64:67], v[164:167], v[182:185], v[64:67]
	v_mfma_f32_16x16x32_bf16 v[52:55], v[60:63], v[194:197], v[52:55]
	v_mfma_f32_16x16x32_bf16 v[48:51], v[164:167], v[194:197], v[48:51]
	v_mfma_f32_16x16x32_bf16 v[36:39], v[60:63], v[202:205], v[36:39]
	v_mfma_f32_16x16x32_bf16 v[32:35], v[164:167], v[202:205], v[32:35]
	v_mfma_f32_16x16x32_bf16 v[12:15], v[60:63], v[210:213], v[12:15]
	v_mfma_f32_16x16x32_bf16 v[8:11], v[164:167], v[210:213], v[8:11]
	s_setprio 0
	s_barrier
	s_add_u32 s38, s38, 0x40080
	s_addc_u32 s39, s39, 0
	s_add_i32 s40, s40, s48
	v_lshl_add_u64 v[56:57], s[38:39], 0, v[136:137]
	s_mov_b32 m0, s40
	s_nop 0
	global_load_lds_dwordx4 v[56:57], off
	v_lshl_add_u64 v[56:57], s[38:39], 0, v[144:145]
	s_add_i32 m0, s40, 0x2000
	s_nop 0
	global_load_lds_dwordx4 v[56:57], off
	s_waitcnt vmcnt(6)
	s_barrier
	s_setprio 1
	v_mfma_f32_16x16x32_bf16 v[24:27], v[214:217], v[168:171], v[24:27]
	v_mfma_f32_16x16x32_bf16 v[60:63], v[218:221], v[182:185], v[24:27]
	v_mfma_f32_16x16x32_bf16 v[24:27], v[222:225], v[168:171], v[28:31]
	v_mfma_f32_16x16x32_bf16 v[56:59], v[226:229], v[182:185], v[24:27]
	v_mfma_f32_16x16x32_bf16 v[24:27], v[214:217], v[190:193], v[44:47]
	v_mfma_f32_16x16x32_bf16 v[44:47], v[218:221], v[194:197], v[24:27]
	v_mfma_f32_16x16x32_bf16 v[24:27], v[222:225], v[190:193], v[40:43]
	v_mfma_f32_16x16x32_bf16 v[20:23], v[214:217], v[198:201], v[20:23]
	v_mfma_f32_16x16x32_bf16 v[16:19], v[222:225], v[198:201], v[16:19]
	v_mfma_f32_16x16x32_bf16 v[4:7], v[214:217], v[206:209], v[4:7]
	v_mfma_f32_16x16x32_bf16 v[0:3], v[222:225], v[206:209], v[0:3]
	v_mfma_f32_16x16x32_bf16 v[40:43], v[226:229], v[194:197], v[24:27]
	v_mfma_f32_16x16x32_bf16 v[20:23], v[218:221], v[202:205], v[20:23]
	v_mfma_f32_16x16x32_bf16 v[16:19], v[226:229], v[202:205], v[16:19]
	v_mfma_f32_16x16x32_bf16 v[4:7], v[218:221], v[210:213], v[4:7]
	v_mfma_f32_16x16x32_bf16 v[0:3], v[226:229], v[210:213], v[0:3]
	s_setprio 0
	s_add_i32 s68, s68, 2
	s_add_u32 s6, s6, 0x100
	s_addc_u32 s7, s7, 0
	s_add_u32 s45, s45, 0x100
	s_addc_u32 s67, s67, 0
	s_cmp_gt_u32 s68, 13
	s_barrier
	s_cbranch_scc0 .LBB0_642
	v_cndmask_b32_e64 v24, 0, 1, s[8:9]
	v_cmp_ne_u32_e64 s[6:7], 1, v24
	s_andn2_b64 vcc, exec, s[8:9]
	s_cbranch_vccnz .LBB0_645
	s_lshl_b64 s[8:9], s[28:29], 14
	v_lshl_add_u64 v[28:29], v[148:149], 0, s[8:9]
	global_load_dwordx4 v[24:27], v[28:29], off offset:16
	s_nop 0
	global_load_dwordx4 v[28:31], v[28:29], off

.LBB0_1259:
	s_cmp_lt_i32 s46, 11
	s_cselect_b64 s[2:3], -1, 0
	s_and_b64 s[8:9], s[2:3], s[0:1]
	s_andn2_b64 vcc, exec, s[8:9]
	s_cbranch_vccnz .LBB0_1478
	s_mov_b32 s0, -1
	v_writelane_b32 v254, s0, 1
	v_mov_b32_e32 v107, v188
	s_movk_i32 s0, 0x80
	s_nop 0
	v_readfirstlane_b32 s6, v107
	v_cmp_gt_i32_e32 vcc, s0, v107
	s_and_saveexec_b64 s[2:3], vcc
	s_cbranch_execz .LBB0_1264
	v_cmp_lt_i32_e32 vcc, 15, v107
	v_mov_b32_e32 v0, v107
	s_and_saveexec_b64 s[4:5], vcc
	s_cbranch_execz .LBB0_1263
	v_cvt_f32_u32_e32 v0, v107
	s_mov_b32 s0, 0x800000
	s_mov_b32 s1, 0x7f800000
	s_mov_b32 s7, 0x40051592
	v_mul_f32_e32 v0, 0x3d800000, v0
	v_cmp_gt_f32_e32 vcc, s0, v0
	s_mov_b32 s0, 0x3f317217
	s_waitcnt lgkmcnt(0)
	v_cndmask_b32_e64 v1, 0, 32, vcc
	v_ldexp_f32 v0, v0, v1
	v_log_f32_e32 v0, v0
	v_mov_b32_e32 v1, 0x41b17218
	v_cndmask_b32_e32 v1, 0, v1, vcc
	v_mul_f32_e32 v2, 0x3f317217, v0
	v_fma_f32 v2, v0, s0, -v2
	v_fmamk_f32 v2, v0, 0x3377d1cf, v2
	v_fmac_f32_e32 v2, 0x3f317217, v0
	v_cmp_lt_f32_e64 s[0:1], |v0|, s1
	s_nop 1
	v_cndmask_b32_e64 v0, v0, v2, s[0:1]
	v_sub_f32_e32 v0, v0, v1
	v_div_scale_f32 v1, s[0:1], s7, s7, v0
	v_rcp_f32_e32 v2, v1
	s_nop 0
	v_fma_f32 v3, -v1, v2, 1.0
	v_fmac_f32_e32 v2, v3, v2
	v_div_scale_f32 v3, vcc, v0, s7, v0
	v_mul_f32_e32 v4, v3, v2
	v_fma_f32 v5, -v1, v4, v3
	v_fmac_f32_e32 v4, v5, v2
	v_fma_f32 v1, -v1, v4, v3
	v_div_fmas_f32 v1, v1, v2, v4
	v_div_fixup_f32 v0, v1, s7, v0
	v_mul_f32_e32 v0, 0x41800000, v0
	v_cvt_i32_f32_e32 v0, v0
	v_min_i32_e32 v0, 15, v0
	v_add_u32_e32 v0, 16, v0

.LBB0_1279:
	s_lshl_b32 s39, s45, 6
	s_and_b32 s8, s2, 3
	v_or_b32_e32 v130, s39, v154
	s_ashr_i32 s51, s50, 31
	s_lshl_b32 s2, s8, 2
	s_lshl_b64 s[46:47], s[50:51], 11
	v_ashrrev_i32_e32 v131, 31, v130
	s_add_i32 s3, s2, s21
	v_lshl_add_u64 v[0:1], s[46:47], 0, v[130:131]
	v_lshlrev_b64 v[2:3], 11, v[0:1]
	s_lshl_b32 s48, s3, 6
	v_lshl_add_u64 v[2:3], s[56:57], 0, v[2:3]
	s_ashr_i32 s49, s48, 31
	v_lshl_add_u64 v[2:3], s[48:49], 1, v[2:3]
	v_mov_b32_e32 v117, v32
	v_lshl_add_u64 v[2:3], v[2:3], 0, v[116:117]
	global_load_dwordx4 v[80:83], v[2:3], off
	global_load_dwordx4 v[84:87], v[2:3], off offset:32
	global_load_dwordx4 v[88:91], v[2:3], off offset:64
	global_load_dwordx4 v[92:95], v[2:3], off offset:96
	v_mov_b64_e32 v[2:3], s[76:77]
	v_mad_u64_u32 v[2:3], s[0:1], v0, s20, v[2:3]
	s_mul_i32 s0, s3, 3
	v_mad_i32_i24 v3, v1, s20, v3
	s_ashr_i32 s1, s0, 31
	v_lshl_add_u64 v[0:1], s[0:1], 2, v[2:3]
	global_load_dwordx3 v[104:106], v[0:1], off
	s_barrier
	v_readlane_b32 s0, v254, 1
	s_nop 3
	s_cmp_eq_u32 s0, s8
	s_cbranch_scc1 .Lfa_btab_skip
	v_writelane_b32 v254, s8, 1
	s_and_saveexec_b64 s[0:1], s[22:23]
	s_cbranch_execz .LBB0_1284
	v_or_b32_e32 v0, s2, v196
	s_mov_b64 s[2:3], 0
	v_mov_b32_e32 v1, v205
	v_mov_b32_e32 v2, v107
	s_branch .LBB0_1282

.Lfa_btab_skip:
	s_lshl_b32 s40, s8, 6
	s_lshl_b64 s[0:1], s[50:51], 16
	s_add_u32 s0, s73, s0
	s_addc_u32 s1, s19, s1
	s_lshl_b32 s2, s8, 7
	s_add_u32 s0, s0, s2
	s_addc_u32 s1, s1, 0
	v_mov_b32_e32 v121, v32
	v_lshl_add_u64 v[0:1], s[0:1], 0, v[120:121]
	s_mov_b64 s[0:1], 0x200000
	v_lshlrev_b64 v[4:5], 1, v[114:115]
	v_lshl_add_u64 v[2:3], v[0:1], 0, s[0:1]
	v_lshl_add_u64 v[6:7], v[0:1], 0, v[4:5]
	v_lshl_add_u64 v[4:5], v[2:3], 0, v[4:5]
	global_load_dwordx4 v[16:19], v[6:7], off
	global_load_dwordx4 v[20:23], v[4:5], off
	v_lshl_add_u64 v[0:1], v[0:1], 0, v[118:119]
	global_load_dwordx4 v[24:27], v[0:1], off
	v_lshl_add_u64 v[0:1], v[2:3], 0, v[118:119]
	global_load_dwordx4 v[28:31], v[0:1], off
	s_lshl_b32 s2, s40, 1
	s_mul_i32 s0, s50, 0x600000
	s_mul_hi_i32 s1, s50, 0x600000
	s_add_u32 s0, s24, s0
	s_addc_u32 s1, s25, s1
	s_add_u32 s0, s0, s2
	s_addc_u32 s1, s1, 0
	v_lshl_add_u64 v[252:253], s[0:1], 0, v[112:113]
	v_lshl_add_u64 v[252:253], v[252:253], 0, v[120:121]
	global_load_dwordx4 v[236:239], v[252:253], off offset:1024
	global_load_dwordx4 v[240:243], v[252:253], off offset:1536
	v_mov_b32_e32 v33, v32
	s_cmp_gt_i32 s45, 15
	v_mov_b32_e32 v34, v32
	v_mov_b32_e32 v35, v32
	v_mov_b32_e32 v36, v32
	v_mov_b32_e32 v37, v32
	v_mov_b32_e32 v38, v32
	v_mov_b32_e32 v39, v32
	v_mov_b32_e32 v40, v32
	v_mov_b32_e32 v41, v32
	v_mov_b32_e32 v42, v32
	v_mov_b32_e32 v43, v32
	v_mov_b32_e32 v44, v32
	v_mov_b32_e32 v45, v32
	v_mov_b32_e32 v46, v32
	v_mov_b32_e32 v47, v32
	v_mov_b64_e32 v[0:1], v[32:33]
	s_cselect_b64 s[30:31], -1, 0
	s_cmp_lt_i32 s45, 16
	s_mov_b32 s3, 0
	v_subrev_u32_e32 v66, 31, v130
	v_mov_b32_e32 v67, 0
	v_mov_b32_e32 v48, 0xff800000
	s_mov_b64 s[34:35], -1
	v_mov_b64_e32 v[2:3], v[34:35]
	v_mov_b64_e32 v[4:5], v[36:37]
	v_mov_b64_e32 v[6:7], v[38:39]
	v_mov_b64_e32 v[8:9], v[40:41]
	v_mov_b64_e32 v[10:11], v[42:43]
	v_mov_b64_e32 v[12:13], v[44:45]
	v_mov_b64_e32 v[14:15], v[46:47]
	s_cselect_b64 s[0:1], -1, 0
	s_waitcnt vmcnt(5)
	ds_write_b128 v195, v[16:19]
	s_waitcnt vmcnt(3)
	ds_write_b128 v195, v[24:27] offset:9216
	ds_write_b128 v195, v[20:23] offset:18432
	s_waitcnt vmcnt(2)
	ds_write_b128 v195, v[28:31] offset:27648
	v_mov_b64_e32 v[16:17], v[32:33]
	v_mov_b64_e32 v[18:19], v[34:35]
	v_mov_b64_e32 v[20:21], v[36:37]
	v_mov_b64_e32 v[22:23], v[38:39]
	v_mov_b64_e32 v[24:25], v[40:41]
	v_mov_b64_e32 v[26:27], v[42:43]
	v_mov_b64_e32 v[28:29], v[44:45]
	v_mov_b64_e32 v[30:31], v[46:47]
	s_waitcnt lgkmcnt(0)
	s_barrier

.LBB0_1639:
	ds_read_b128 v[16:19], v212
	ds_read_b128 v[20:23], v212 offset:1024
	ds_read_b128 v[24:27], v212 offset:2048
	ds_read_b128 v[68:71], v212 offset:3072
	s_add_u32 s28, s8, 0x100
	s_addc_u32 s29, s9, 0
	s_cmp_eq_u32 s67, 12
	s_cselect_b32 s35, s59, s29
	s_cselect_b32 s34, s60, s28
	s_cselect_b32 s31, s11, s63
	s_cselect_b32 s30, s61, s62
	v_lshl_add_u64 v[176:177], s[8:9], 0, v[204:205]
	s_add_i32 m0, s42, 0xc000
	ds_read_b128 v[96:99], v213
	ds_read_b128 v[148:151], v213 offset:1024
	ds_read_b128 v[152:155], v213 offset:2048
	ds_read_b128 v[156:159], v213 offset:3072
	ds_read_b128 v[160:163], v213 offset:4096
	ds_read_b128 v[164:167], v213 offset:5120
	ds_read_b128 v[168:171], v213 offset:6144
	ds_read_b128 v[172:175], v213 offset:7168
	global_load_lds_dwordx4 v[176:177], off
	v_lshl_add_u64 v[176:177], s[8:9], 0, v[206:207]
	s_add_i32 m0, s42, 0xe000
	s_nop 0
	global_load_lds_dwordx4 v[176:177], off
	s_waitcnt lgkmcnt(8)
	s_barrier
	s_waitcnt lgkmcnt(0)
	s_setprio 1
	s_waitcnt lgkmcnt(0)
	v_mfma_f32_16x16x32_bf16 v[112:115], v[16:19], v[96:99], v[112:115]
	v_mfma_f32_16x16x32_bf16 v[40:43], v[24:27], v[96:99], v[40:43]
	v_mfma_f32_16x16x32_bf16 v[108:111], v[16:19], v[152:155], v[108:111]
	v_mfma_f32_16x16x32_bf16 v[36:39], v[24:27], v[152:155], v[36:39]
	v_mfma_f32_16x16x32_bf16 v[144:147], v[16:19], v[160:163], v[144:147]
	v_mfma_f32_16x16x32_bf16 v[140:143], v[24:27], v[160:163], v[140:143]
	v_mfma_f32_16x16x32_bf16 v[136:139], v[16:19], v[168:171], v[136:139]
	v_mfma_f32_16x16x32_bf16 v[132:135], v[24:27], v[168:171], v[132:135]
	v_mfma_f32_16x16x32_bf16 v[112:115], v[20:23], v[148:151], v[112:115]
	v_mfma_f32_16x16x32_bf16 v[40:43], v[68:71], v[148:151], v[40:43]
	v_mfma_f32_16x16x32_bf16 v[108:111], v[20:23], v[156:159], v[108:111]
	v_mfma_f32_16x16x32_bf16 v[36:39], v[68:71], v[156:159], v[36:39]
	v_mfma_f32_16x16x32_bf16 v[144:147], v[20:23], v[164:167], v[144:147]
	v_mfma_f32_16x16x32_bf16 v[140:143], v[68:71], v[164:167], v[140:143]
	v_mfma_f32_16x16x32_bf16 v[136:139], v[20:23], v[172:175], v[136:139]
	v_mfma_f32_16x16x32_bf16 v[132:135], v[68:71], v[172:175], v[132:135]
	s_setprio 0
	s_barrier
	s_add_i32 s8, s52, s41
	v_lshl_add_u64 v[222:223], s[30:31], 0, v[192:193]
	s_mov_b32 m0, s8
	ds_read_b128 v[176:179], v214
	ds_read_b128 v[180:183], v214 offset:1024
	ds_read_b128 v[184:187], v214 offset:2048
	ds_read_b128 v[218:221], v214 offset:3072
	global_load_lds_dwordx4 v[222:223], off
	v_lshl_add_u64 v[224:225], s[30:31], 0, v[198:199]
	s_add_i32 m0, s8, 0x2000
	s_nop 0
	global_load_lds_dwordx4 v[224:225], off
	s_barrier
	s_waitcnt lgkmcnt(0)
	s_setprio 1
	s_waitcnt lgkmcnt(0)
	v_mfma_f32_16x16x32_bf16 v[104:107], v[176:179], v[96:99], v[104:107]
	v_mfma_f32_16x16x32_bf16 v[32:35], v[184:187], v[96:99], v[32:35]
	v_mfma_f32_16x16x32_bf16 v[28:31], v[184:187], v[152:155], v[28:31]
	v_mfma_f32_16x16x32_bf16 v[80:83], v[176:179], v[160:163], v[80:83]
	v_mfma_f32_16x16x32_bf16 v[92:95], v[184:187], v[160:163], v[92:95]
	v_mfma_f32_16x16x32_bf16 v[84:87], v[176:179], v[168:171], v[84:87]
	v_mfma_f32_16x16x32_bf16 v[88:91], v[184:187], v[168:171], v[88:91]
	v_mfma_f32_16x16x32_bf16 v[104:107], v[180:183], v[148:151], v[104:107]
	v_mfma_f32_16x16x32_bf16 v[32:35], v[218:221], v[148:151], v[32:35]
	v_mfma_f32_16x16x32_bf16 v[96:99], v[176:179], v[152:155], v[100:103]
	v_mfma_f32_16x16x32_bf16 v[28:31], v[218:221], v[156:159], v[28:31]
	v_mfma_f32_16x16x32_bf16 v[80:83], v[180:183], v[164:167], v[80:83]
	v_mfma_f32_16x16x32_bf16 v[92:95], v[218:221], v[164:167], v[92:95]
	v_mfma_f32_16x16x32_bf16 v[84:87], v[180:183], v[172:175], v[84:87]
	v_mfma_f32_16x16x32_bf16 v[88:91], v[218:221], v[172:175], v[88:91]
	v_mfma_f32_16x16x32_bf16 v[96:99], v[180:183], v[156:159], v[96:99]
	s_setprio 0
	s_mov_b32 m0, s42
	v_lshl_add_u64 v[226:227], s[34:35], 0, v[194:195]
	s_barrier
	ds_read_b128 v[100:103], v213 offset:16384
	ds_read_b128 v[148:151], v213 offset:17408
	ds_read_b128 v[152:155], v213 offset:18432
	ds_read_b128 v[156:159], v213 offset:19456
	ds_read_b128 v[160:163], v213 offset:20480
	ds_read_b128 v[164:167], v213 offset:21504
	ds_read_b128 v[168:171], v213 offset:22528
	ds_read_b128 v[172:175], v213 offset:23552
	global_load_lds_dwordx4 v[226:227], off
	v_lshl_add_u64 v[228:229], s[34:35], 0, v[196:197]
	s_mov_b32 m0, s43
	s_nop 0
	global_load_lds_dwordx4 v[228:229], off
	s_barrier
	s_waitcnt lgkmcnt(0)
	s_setprio 1
	s_waitcnt lgkmcnt(0)
	v_mfma_f32_16x16x32_bf16 v[76:79], v[16:19], v[100:103], v[76:79]
	v_mfma_f32_16x16x32_bf16 v[12:15], v[24:27], v[100:103], v[12:15]
	v_mfma_f32_16x16x32_bf16 v[72:75], v[16:19], v[152:155], v[72:75]
	v_mfma_f32_16x16x32_bf16 v[8:11], v[24:27], v[152:155], v[8:11]
	v_mfma_f32_16x16x32_bf16 v[128:131], v[16:19], v[160:163], v[128:131]
	v_mfma_f32_16x16x32_bf16 v[124:127], v[24:27], v[160:163], v[124:127]
	v_mfma_f32_16x16x32_bf16 v[16:19], v[16:19], v[168:171], v[120:123]
	v_mfma_f32_16x16x32_bf16 v[76:79], v[20:23], v[148:151], v[76:79]
	v_mfma_f32_16x16x32_bf16 v[12:15], v[68:71], v[148:151], v[12:15]
	v_mfma_f32_16x16x32_bf16 v[72:75], v[20:23], v[156:159], v[72:75]
	v_mfma_f32_16x16x32_bf16 v[8:11], v[68:71], v[156:159], v[8:11]
	v_mfma_f32_16x16x32_bf16 v[128:131], v[20:23], v[164:167], v[128:131]
	v_mfma_f32_16x16x32_bf16 v[124:127], v[68:71], v[164:167], v[124:127]
	v_mfma_f32_16x16x32_bf16 v[16:19], v[20:23], v[172:175], v[16:19]
	v_mfma_f32_16x16x32_bf16 v[20:23], v[24:27], v[168:171], v[116:119]
	v_mfma_f32_16x16x32_bf16 v[20:23], v[68:71], v[172:175], v[20:23]
	s_setprio 0
	s_barrier
	s_add_u32 s8, s30, 0x40000
	s_addc_u32 s9, s31, 0
	s_add_i32 s68, s53, s41
	v_lshl_add_u64 v[24:25], s[8:9], 0, v[192:193]
	s_mov_b32 m0, s68
	s_nop 0
	global_load_lds_dwordx4 v[24:25], off
	v_lshl_add_u64 v[24:25], s[8:9], 0, v[198:199]
	s_add_i32 m0, s68, 0x2000
	s_nop 0
	global_load_lds_dwordx4 v[24:25], off
	s_waitcnt vmcnt(6)
	s_barrier
	s_setprio 1
	v_mfma_f32_16x16x32_bf16 v[4:7], v[184:187], v[100:103], v[4:7]
	v_mfma_f32_16x16x32_bf16 v[60:63], v[176:179], v[152:155], v[60:63]
	v_mfma_f32_16x16x32_bf16 v[0:3], v[184:187], v[152:155], v[0:3]
	v_mfma_f32_16x16x32_bf16 v[44:47], v[176:179], v[160:163], v[44:47]
	v_mfma_f32_16x16x32_bf16 v[48:51], v[184:187], v[160:163], v[48:51]
	v_mfma_f32_16x16x32_bf16 v[52:55], v[176:179], v[168:171], v[52:55]
	v_mfma_f32_16x16x32_bf16 v[56:59], v[184:187], v[168:171], v[56:59]
	v_mfma_f32_16x16x32_bf16 v[24:27], v[176:179], v[100:103], v[64:67]
	v_mfma_f32_16x16x32_bf16 v[4:7], v[218:221], v[148:151], v[4:7]
	v_mfma_f32_16x16x32_bf16 v[60:63], v[180:183], v[156:159], v[60:63]
	v_mfma_f32_16x16x32_bf16 v[0:3], v[218:221], v[156:159], v[0:3]
	v_mfma_f32_16x16x32_bf16 v[44:47], v[180:183], v[164:167], v[44:47]
	v_mfma_f32_16x16x32_bf16 v[48:51], v[218:221], v[164:167], v[48:51]
	v_mfma_f32_16x16x32_bf16 v[52:55], v[180:183], v[172:175], v[52:55]
	v_mfma_f32_16x16x32_bf16 v[56:59], v[218:221], v[172:175], v[56:59]
	v_mfma_f32_16x16x32_bf16 v[24:27], v[180:183], v[148:151], v[24:27]
	s_setprio 0
	s_add_i32 s68, 0, 0x18000
	v_add_u32_e32 v100, s68, v208
	s_barrier
	ds_read_b128 v[64:67], v100
	ds_read_b128 v[68:71], v100 offset:1024
	ds_read_b128 v[116:119], v100 offset:2048
	ds_read_b128 v[148:151], v100 offset:3072
	s_add_u32 s8, s34, 0x40000
	s_addc_u32 s9, s35, 0
	s_mov_b32 m0, s44
	v_lshl_add_u64 v[176:177], s[8:9], 0, v[194:195]
	ds_read_b128 v[100:103], v213 offset:32768
	ds_read_b128 v[120:123], v213 offset:33792
	ds_read_b128 v[152:155], v213 offset:34816
	ds_read_b128 v[156:159], v213 offset:35840
	ds_read_b128 v[160:163], v213 offset:36864
	ds_read_b128 v[164:167], v213 offset:37888
	ds_read_b128 v[168:171], v213 offset:38912
	ds_read_b128 v[172:175], v213 offset:39936
	global_load_lds_dwordx4 v[176:177], off
	v_lshl_add_u64 v[176:177], s[8:9], 0, v[196:197]
	s_mov_b32 m0, s45
	s_nop 0
	global_load_lds_dwordx4 v[176:177], off
	s_waitcnt lgkmcnt(8)
	s_barrier
	s_waitcnt lgkmcnt(0)
	s_setprio 1
	s_waitcnt lgkmcnt(0)
	v_mfma_f32_16x16x32_bf16 v[112:115], v[64:67], v[100:103], v[112:115]
	v_mfma_f32_16x16x32_bf16 v[40:43], v[116:119], v[100:103], v[40:43]
	v_mfma_f32_16x16x32_bf16 v[108:111], v[64:67], v[152:155], v[108:111]
	v_mfma_f32_16x16x32_bf16 v[36:39], v[116:119], v[152:155], v[36:39]
	v_mfma_f32_16x16x32_bf16 v[144:147], v[64:67], v[160:163], v[144:147]
	v_mfma_f32_16x16x32_bf16 v[140:143], v[116:119], v[160:163], v[140:143]
	v_mfma_f32_16x16x32_bf16 v[136:139], v[64:67], v[168:171], v[136:139]
	v_mfma_f32_16x16x32_bf16 v[132:135], v[116:119], v[168:171], v[132:135]
	v_mfma_f32_16x16x32_bf16 v[112:115], v[68:71], v[120:123], v[112:115]
	v_mfma_f32_16x16x32_bf16 v[40:43], v[148:151], v[120:123], v[40:43]
	v_mfma_f32_16x16x32_bf16 v[108:111], v[68:71], v[156:159], v[108:111]
	v_mfma_f32_16x16x32_bf16 v[36:39], v[148:151], v[156:159], v[36:39]
	v_mfma_f32_16x16x32_bf16 v[144:147], v[68:71], v[164:167], v[144:147]
	v_mfma_f32_16x16x32_bf16 v[140:143], v[148:151], v[164:167], v[140:143]
	v_mfma_f32_16x16x32_bf16 v[136:139], v[68:71], v[172:175], v[136:139]
	v_mfma_f32_16x16x32_bf16 v[132:135], v[148:151], v[172:175], v[132:135]
	s_setprio 0
	s_barrier
	s_add_i32 s34, 0, 0x1c000
	s_add_i32 s8, s68, s41
	v_add_u32_e32 v217, s34, v208
	v_lshl_add_u64 v[222:223], v[222:223], 0, s[18:19]
	s_mov_b32 m0, s8
	ds_read_b128 v[176:179], v217
	ds_read_b128 v[180:183], v217 offset:1024
	ds_read_b128 v[184:187], v217 offset:2048
	ds_read_b128 v[218:221], v217 offset:3072
	global_load_lds_dwordx4 v[222:223], off
	v_lshl_add_u64 v[222:223], v[224:225], 0, s[18:19]
	s_add_i32 m0, s8, 0x2000
	s_nop 0
	global_load_lds_dwordx4 v[222:223], off
	s_barrier
	s_waitcnt lgkmcnt(0)
	s_setprio 1
	s_waitcnt lgkmcnt(0)
	v_mfma_f32_16x16x32_bf16 v[104:107], v[176:179], v[100:103], v[104:107]
	v_mfma_f32_16x16x32_bf16 v[32:35], v[184:187], v[100:103], v[32:35]
	v_mfma_f32_16x16x32_bf16 v[96:99], v[176:179], v[152:155], v[96:99]
	v_mfma_f32_16x16x32_bf16 v[28:31], v[184:187], v[152:155], v[28:31]
	v_mfma_f32_16x16x32_bf16 v[80:83], v[176:179], v[160:163], v[80:83]
	v_mfma_f32_16x16x32_bf16 v[92:95], v[184:187], v[160:163], v[92:95]
	v_mfma_f32_16x16x32_bf16 v[84:87], v[176:179], v[168:171], v[84:87]
	v_mfma_f32_16x16x32_bf16 v[88:91], v[184:187], v[168:171], v[88:91]
	v_mfma_f32_16x16x32_bf16 v[104:107], v[180:183], v[120:123], v[104:107]
	v_mfma_f32_16x16x32_bf16 v[32:35], v[218:221], v[120:123], v[32:35]
	v_mfma_f32_16x16x32_bf16 v[100:103], v[180:183], v[156:159], v[96:99]
	v_mfma_f32_16x16x32_bf16 v[28:31], v[218:221], v[156:159], v[28:31]
	v_mfma_f32_16x16x32_bf16 v[80:83], v[180:183], v[164:167], v[80:83]
	v_mfma_f32_16x16x32_bf16 v[92:95], v[218:221], v[164:167], v[92:95]
	v_mfma_f32_16x16x32_bf16 v[84:87], v[180:183], v[172:175], v[84:87]
	v_mfma_f32_16x16x32_bf16 v[88:91], v[218:221], v[172:175], v[88:91]
	s_setprio 0
	s_mov_b32 m0, s49
	v_lshl_add_u64 v[120:121], v[226:227], 0, s[18:19]
	s_barrier
	ds_read_b128 v[96:99], v213 offset:49152
	ds_read_b128 v[152:155], v213 offset:50176
	ds_read_b128 v[156:159], v213 offset:51200
	ds_read_b128 v[160:163], v213 offset:52224
	ds_read_b128 v[164:167], v213 offset:53248
	ds_read_b128 v[168:171], v213 offset:54272
	ds_read_b128 v[172:175], v213 offset:55296
	ds_read_b128 v[222:225], v213 offset:56320
	global_load_lds_dwordx4 v[120:121], off
	v_lshl_add_u64 v[120:121], v[228:229], 0, s[18:19]
	s_mov_b32 m0, s50
	s_nop 0
	global_load_lds_dwordx4 v[120:121], off
	s_barrier
	s_waitcnt lgkmcnt(0)
	s_setprio 1
	s_waitcnt lgkmcnt(0)
	v_mfma_f32_16x16x32_bf16 v[120:123], v[64:67], v[164:167], v[128:131]
	v_mfma_f32_16x16x32_bf16 v[128:131], v[68:71], v[168:171], v[120:123]
	v_mfma_f32_16x16x32_bf16 v[120:123], v[116:119], v[164:167], v[124:127]
	v_mfma_f32_16x16x32_bf16 v[16:19], v[64:67], v[172:175], v[16:19]
	v_mfma_f32_16x16x32_bf16 v[76:79], v[64:67], v[96:99], v[76:79]
	v_mfma_f32_16x16x32_bf16 v[12:15], v[116:119], v[96:99], v[12:15]
	v_mfma_f32_16x16x32_bf16 v[72:75], v[64:67], v[156:159], v[72:75]
	v_mfma_f32_16x16x32_bf16 v[8:11], v[116:119], v[156:159], v[8:11]
	v_mfma_f32_16x16x32_bf16 v[124:127], v[148:151], v[168:171], v[120:123]
	v_mfma_f32_16x16x32_bf16 v[120:123], v[68:71], v[222:225], v[16:19]
	v_mfma_f32_16x16x32_bf16 v[16:19], v[116:119], v[172:175], v[20:23]
	v_mfma_f32_16x16x32_bf16 v[76:79], v[68:71], v[152:155], v[76:79]
	v_mfma_f32_16x16x32_bf16 v[12:15], v[148:151], v[152:155], v[12:15]
	v_mfma_f32_16x16x32_bf16 v[72:75], v[68:71], v[160:163], v[72:75]
	v_mfma_f32_16x16x32_bf16 v[8:11], v[148:151], v[160:163], v[8:11]
	v_mfma_f32_16x16x32_bf16 v[116:119], v[148:151], v[222:225], v[16:19]
	s_setprio 0
	s_barrier
	s_add_u32 s8, s30, 0x40080
	s_addc_u32 s9, s31, 0
	s_add_i32 s30, s34, s41
	v_lshl_add_u64 v[16:17], s[8:9], 0, v[192:193]
	s_mov_b32 m0, s30
	s_nop 0
	global_load_lds_dwordx4 v[16:17], off
	v_lshl_add_u64 v[16:17], s[8:9], 0, v[198:199]
	s_add_i32 m0, s30, 0x2000
	s_nop 0
	global_load_lds_dwordx4 v[16:17], off
	s_waitcnt vmcnt(6)
	s_barrier
	s_setprio 1
	v_mfma_f32_16x16x32_bf16 v[16:19], v[176:179], v[96:99], v[24:27]
	v_mfma_f32_16x16x32_bf16 v[64:67], v[180:183], v[152:155], v[16:19]
	v_mfma_f32_16x16x32_bf16 v[16:19], v[176:179], v[156:159], v[60:63]
	v_mfma_f32_16x16x32_bf16 v[60:63], v[180:183], v[160:163], v[16:19]
	v_mfma_f32_16x16x32_bf16 v[16:19], v[176:179], v[164:167], v[44:47]
	v_mfma_f32_16x16x32_bf16 v[44:47], v[180:183], v[168:171], v[16:19]
	v_mfma_f32_16x16x32_bf16 v[16:19], v[184:187], v[164:167], v[48:51]
	v_mfma_f32_16x16x32_bf16 v[48:51], v[218:221], v[168:171], v[16:19]
	v_mfma_f32_16x16x32_bf16 v[16:19], v[176:179], v[172:175], v[52:55]
	v_mfma_f32_16x16x32_bf16 v[4:7], v[184:187], v[96:99], v[4:7]
	v_mfma_f32_16x16x32_bf16 v[0:3], v[184:187], v[156:159], v[0:3]
	v_mfma_f32_16x16x32_bf16 v[52:55], v[180:183], v[222:225], v[16:19]
	v_mfma_f32_16x16x32_bf16 v[16:19], v[184:187], v[172:175], v[56:59]
	v_mfma_f32_16x16x32_bf16 v[4:7], v[218:221], v[152:155], v[4:7]
	v_mfma_f32_16x16x32_bf16 v[0:3], v[218:221], v[160:163], v[0:3]
	v_mfma_f32_16x16x32_bf16 v[56:59], v[218:221], v[222:225], v[16:19]
	s_setprio 0
	s_add_i32 s67, s67, 2
	s_add_u32 s62, s62, 0x100
	s_addc_u32 s63, s63, 0
	s_cmp_gt_u32 s67, 13
	s_mov_b64 s[8:9], s[28:29]
	s_barrier
	s_cbranch_scc0 .LBB0_1639
	v_cndmask_b32_e64 v16, 0, 1, s[26:27]
	v_cmp_ne_u32_e64 s[8:9], 1, v16
	s_andn2_b64 vcc, exec, s[26:27]
	s_cbranch_vccnz .LBB0_1644
	v_mov_b32_e32 v16, 0
	v_mov_b32_e32 v17, 0
	v_mov_b32_e32 v18, 0
	v_mov_b32_e32 v19, 0
	s_and_saveexec_b64 s[26:27], s[2:3]
	s_cbranch_execz .LBB0_1643
	s_lshl_b32 s28, s10, 7
	s_ashr_i32 s29, s28, 31
	v_lshl_add_u64 v[16:17], s[28:29], 2, v[202:203]
	global_load_dwordx4 v[16:19], v[16:17], off

	.amdhsa_kernel _Z6mk_fwd4Args
		.amdhsa_group_segment_fixed_size 0
		.amdhsa_private_segment_fixed_size 0
		.amdhsa_kernarg_size 448
		.amdhsa_user_sgpr_count 2
		.amdhsa_user_sgpr_dispatch_ptr 0
		.amdhsa_user_sgpr_queue_ptr 0
		.amdhsa_user_sgpr_kernarg_segment_ptr 1
		.amdhsa_user_sgpr_dispatch_id 0
		.amdhsa_user_sgpr_kernarg_preload_length 0
		.amdhsa_user_sgpr_kernarg_preload_offset 0
		.amdhsa_user_sgpr_private_segment_size 0
		.amdhsa_uses_dynamic_stack 0
		.amdhsa_enable_private_segment 0
		.amdhsa_system_sgpr_workgroup_id_x 1
		.amdhsa_system_sgpr_workgroup_id_y 0
		.amdhsa_system_sgpr_workgroup_id_z 0
		.amdhsa_system_sgpr_workgroup_info 0
		.amdhsa_system_vgpr_workitem_id 2
		.amdhsa_next_free_vgpr 256
		.amdhsa_next_free_sgpr 98
		.amdhsa_accum_offset 256
		.amdhsa_reserve_vcc 1
		.amdhsa_float_round_mode_32 0
		.amdhsa_float_round_mode_16_64 0
		.amdhsa_float_denorm_mode_32 3
		.amdhsa_float_denorm_mode_16_64 3
		.amdhsa_dx10_clamp 1
		.amdhsa_ieee_mode 1
		.amdhsa_fp16_overflow 0
		.amdhsa_tg_split 0
		.amdhsa_exception_fp_ieee_invalid_op 0
		.amdhsa_exception_fp_denorm_src 0
		.amdhsa_exception_fp_ieee_div_zero 0
		.amdhsa_exception_fp_ieee_overflow 0
		.amdhsa_exception_fp_ieee_underflow 0
		.amdhsa_exception_fp_ieee_inexact 0
		.amdhsa_exception_int_div_zero 0
	.end_amdhsa_kernel

amdhsa.kernels:
  - .agpr_count:     0
    .args:
      - .offset:         0
        .size:           192
        .value_kind:     by_value
      - .offset:         192
        .size:           4
        .value_kind:     hidden_block_count_x
      - .offset:         196
        .size:           4
        .value_kind:     hidden_block_count_y
      - .offset:         200
        .size:           4
        .value_kind:     hidden_block_count_z
      - .offset:         204
        .size:           2
        .value_kind:     hidden_group_size_x
      - .offset:         206
        .size:           2
        .value_kind:     hidden_group_size_y
      - .offset:         208
        .size:           2
        .value_kind:     hidden_group_size_z
      - .offset:         210
        .size:           2
        .value_kind:     hidden_remainder_x
      - .offset:         212
        .size:           2
        .value_kind:     hidden_remainder_y
      - .offset:         214
        .size:           2
        .value_kind:     hidden_remainder_z
      - .offset:         232
        .size:           8
        .value_kind:     hidden_global_offset_x
      - .offset:         240
        .size:           8
        .value_kind:     hidden_global_offset_y
      - .offset:         248
        .size:           8
        .value_kind:     hidden_global_offset_z
      - .offset:         256
        .size:           2
        .value_kind:     hidden_grid_dims
      - .offset:         280
        .size:           8
        .value_kind:     hidden_multigrid_sync_arg
      - .offset:         312
        .size:           4
        .value_kind:     hidden_dynamic_lds_size
    .group_segment_fixed_size: 0
    .kernarg_segment_align: 8
    .kernarg_segment_size: 448
    .language:       OpenCL C
    .language_version:
      - 2
      - 0
    .max_flat_workgroup_size: 512
    .name:           _Z6mk_fwd4Args
    .private_segment_fixed_size: 0
    .sgpr_count:     104
    .sgpr_spill_count: 123
    .symbol:         _Z6mk_fwd4Args.kd
    .uniform_work_group_size: 1
    .uses_dynamic_stack: false
    .vgpr_count:     256
    .vgpr_spill_count: 0
    .wavefront_size: 64
